# v33 + nt cache policy on the once-read residual-row and split-K partial loads of the norm phases and on the final f32 output stores
# speedup vs baseline: 1.0117x; 1.0103x over previous
; #define LAS __attribute__((address_space(3)))
; __device__ __forceinline__ u32x2 f32x4_to_h4(f32x4 v) { return __builtin_bit_cast(u32x2, __builtin_convertvector(v, f16x4)); }
; template <bool COMBINE, bool SRC_F32>
; __device__ __forceinline__ void norm_phase(LAS unsigned char* lds, const void* src_lat, const void* src_ctx, _Float16* xw_ctx, const float* part, int nrows, const float* g, const float* modl, int shift_idx, int scale_idx, bf16* HN, int tid, int lane, int wave) {
;     const int gw = blockIdx.x * 8 + wave, NGW = gridDim.x * 8;
;     LAS _Float16* Gs = (LAS _Float16*)lds;
;     LAS _Float16* Ss = Gs + 9 * D;
;     {
;         const f32x4 gg = *(const f32x4*)(g + 4 * tid);
;         f32x4 s1[9], s0[9];
; #pragma unroll
;         for (int r = 0; r < 9; ++r) { s1[r] = *(const f32x4*)(modl + (size_t)r * DMODW + scale_idx * D + 4 * tid); s0[r] = *(const f32x4*)(modl + (size_t)r * DMODW + shift_idx * D + 4 * tid); }
; #pragma unroll
;         for (int r = 0; r < 9; ++r) { *(LAS u32x2*)(Gs + r * D + 4 * tid) = f32x4_to_h4(gg * (1.0f + s1[r])); *(LAS u32x2*)(Ss + r * D + 4 * tid) = f32x4_to_h4(s0[r]); }
;     }
.LBB0_460:
	s_cmp_lt_i32 s90, 5
	s_cselect_b64 s[2:3], -1, 0
	s_and_b64 s[0:1], s[2:3], s[0:1]
	s_andn2_b64 vcc, exec, s[0:1]
	s_cbranch_vccnz .LBB0_473
	v_readlane_b32 s8, v253, 10
	s_waitcnt vmcnt(0)
	v_lshlrev_b32_e32 v34, 4, v0
	v_mov_b32_e32 v35, 0
	v_readlane_b32 s20, v253, 22
	v_readlane_b32 s21, v253, 23
	v_lshl_add_u64 v[76:77], s[88:89], 0, v[34:35]
	s_add_u32 s4, s88, 0x18400000
	v_lshl_add_u64 v[2:3], s[20:21], 0, v[34:35]
	v_add_co_u32_e32 v2, vcc, 0x2000, v2
	s_addc_u32 s5, s89, 0
	s_nop 0
	v_addc_co_u32_e32 v3, vcc, 0, v3, vcc
	v_add_co_u32_e32 v6, vcc, 0x108000, v76
	global_load_dwordx4 v[2:5], v[2:3], off
	s_nop 0
	v_addc_co_u32_e32 v7, vcc, 0, v77, vcc
	v_add_co_u32_e32 v10, vcc, 0x106000, v76
	s_lshl_b32 s0, s86, 3
	s_nop 0
	v_addc_co_u32_e32 v11, vcc, 0, v77, vcc
	v_add_co_u32_e32 v14, vcc, 0x11a000, v76
	global_load_dwordx4 v[6:9], v[6:7], off
	s_nop 0
	global_load_dwordx4 v[10:13], v[10:11], off
	v_addc_co_u32_e32 v15, vcc, 0, v77, vcc
	v_add_co_u32_e32 v18, vcc, 0x118000, v76
	v_readlane_b32 s1, v253, 31
	s_nop 0
	v_addc_co_u32_e32 v19, vcc, 0, v77, vcc
	v_add_co_u32_e32 v22, vcc, 0x12c000, v76
	global_load_dwordx4 v[14:17], v[14:15], off
	s_nop 0
	global_load_dwordx4 v[18:21], v[18:19], off
	v_addc_co_u32_e32 v23, vcc, 0, v77, vcc
	v_add_co_u32_e32 v26, vcc, 0x12a000, v76
	s_add_i32 s0, s1, s0
	s_nop 0
	v_addc_co_u32_e32 v27, vcc, 0, v77, vcc
	v_add_co_u32_e32 v30, vcc, 0x13e000, v76
	global_load_dwordx4 v[22:25], v[22:23], off
	s_nop 0
	global_load_dwordx4 v[26:29], v[26:27], off
	v_addc_co_u32_e32 v31, vcc, 0, v77, vcc
	v_add_co_u32_e32 v36, vcc, 0x13c000, v76
	v_add_u32_e32 v34, 0x9000, v228
	s_nop 0
	v_addc_co_u32_e32 v37, vcc, 0, v77, vcc
	v_add_co_u32_e32 v40, vcc, 0x150000, v76
	global_load_dwordx4 v[30:33], v[30:31], off
	s_nop 0
	global_load_dwordx4 v[36:39], v[36:37], off
	v_addc_co_u32_e32 v41, vcc, 0, v77, vcc
	v_add_co_u32_e32 v44, vcc, 0x14e000, v76
	s_cmpk_lt_i32 s0, 0x4800
	s_nop 0
	v_addc_co_u32_e32 v45, vcc, 0, v77, vcc
	v_add_co_u32_e32 v48, vcc, 0x162000, v76
	global_load_dwordx4 v[40:43], v[40:41], off
	s_nop 0
	global_load_dwordx4 v[44:47], v[44:45], off
	v_addc_co_u32_e32 v49, vcc, 0, v77, vcc
	v_add_co_u32_e32 v52, vcc, 0x160000, v76
	s_cselect_b64 s[6:7], -1, 0
	s_nop 0
	v_addc_co_u32_e32 v53, vcc, 0, v77, vcc
	v_add_co_u32_e32 v56, vcc, 0x174000, v76
	global_load_dwordx4 v[48:51], v[48:49], off
	s_nop 0
	global_load_dwordx4 v[52:55], v[52:53], off
	v_addc_co_u32_e32 v57, vcc, 0, v77, vcc
	v_add_co_u32_e32 v60, vcc, 0x172000, v76
	s_cmpk_gt_i32 s0, 0x47ff
	s_nop 0
	v_addc_co_u32_e32 v61, vcc, 0, v77, vcc
	v_add_co_u32_e32 v64, vcc, 0x186000, v76
	global_load_dwordx4 v[56:59], v[56:57], off
	s_nop 0
	global_load_dwordx4 v[60:63], v[60:61], off
	v_addc_co_u32_e32 v65, vcc, 0, v77, vcc
	v_add_co_u32_e32 v68, vcc, 0x184000, v76
	global_load_dwordx4 v[64:67], v[64:65], off
	s_nop 0
	v_addc_co_u32_e32 v69, vcc, 0, v77, vcc
	v_add_co_u32_e32 v72, vcc, 0x198000, v76
	global_load_dwordx4 v[68:71], v[68:69], off
	s_nop 0
	v_addc_co_u32_e32 v73, vcc, 0, v77, vcc
	global_load_dwordx4 v[72:75], v[72:73], off
	v_add_co_u32_e32 v76, vcc, 0x196000, v76
	v_readlane_b32 s9, v253, 11
	s_nop 0
	v_addc_co_u32_e32 v77, vcc, 0, v77, vcc
	global_load_dwordx4 v[76:79], v[76:77], off
	s_waitcnt vmcnt(17)
	v_pk_add_f32 v[8:9], v[8:9], 1.0 op_sel_hi:[1,0]
	v_pk_add_f32 v[6:7], v[6:7], 1.0 op_sel_hi:[1,0]
	v_pk_mul_f32 v[8:9], v[4:5], v[8:9]
	v_pk_mul_f32 v[6:7], v[2:3], v[6:7]
	v_cvt_pk_f16_f32 v9, v8, v9
	v_cvt_pk_f16_f32 v8, v6, v7
	s_waitcnt vmcnt(16)
	v_cvt_pk_f16_f32 v7, v12, v13
	v_cvt_pk_f16_f32 v6, v10, v11
	v_readlane_b32 s10, v253, 12
	s_waitcnt vmcnt(15)
	v_pk_add_f32 v[10:11], v[16:17], 1.0 op_sel_hi:[1,0]
	v_pk_add_f32 v[12:13], v[14:15], 1.0 op_sel_hi:[1,0]
	v_pk_mul_f32 v[10:11], v[4:5], v[10:11]
	v_pk_mul_f32 v[12:13], v[2:3], v[12:13]
	v_cvt_pk_f16_f32 v11, v10, v11
	v_cvt_pk_f16_f32 v10, v12, v13
	ds_write2st64_b64 v228, v[8:9], v[10:11] offset1:8
	s_waitcnt vmcnt(14)
	v_cvt_pk_f16_f32 v9, v20, v21
	v_cvt_pk_f16_f32 v8, v18, v19
	v_readlane_b32 s11, v253, 13
	s_waitcnt vmcnt(13)
	v_pk_add_f32 v[10:11], v[24:25], 1.0 op_sel_hi:[1,0]
	v_pk_add_f32 v[12:13], v[22:23], 1.0 op_sel_hi:[1,0]
	v_pk_mul_f32 v[10:11], v[4:5], v[10:11]
	v_pk_mul_f32 v[12:13], v[2:3], v[12:13]
	v_cvt_pk_f16_f32 v11, v10, v11
	v_cvt_pk_f16_f32 v10, v12, v13
	s_waitcnt vmcnt(12)
	v_cvt_pk_f16_f32 v13, v28, v29
	v_cvt_pk_f16_f32 v12, v26, v27
	ds_write2st64_b64 v228, v[8:9], v[12:13] offset0:80 offset1:88
	v_readlane_b32 s12, v253, 14
	s_waitcnt vmcnt(11)
	v_pk_add_f32 v[8:9], v[32:33], 1.0 op_sel_hi:[1,0]
	v_pk_add_f32 v[12:13], v[30:31], 1.0 op_sel_hi:[1,0]
	v_pk_mul_f32 v[8:9], v[4:5], v[8:9]
	v_pk_mul_f32 v[12:13], v[2:3], v[12:13]
	v_cvt_pk_f16_f32 v9, v8, v9
	v_cvt_pk_f16_f32 v8, v12, v13
	ds_write2st64_b64 v228, v[10:11], v[8:9] offset0:16 offset1:24
	s_waitcnt vmcnt(10)
	v_cvt_pk_f16_f32 v9, v38, v39
	v_cvt_pk_f16_f32 v8, v36, v37
	v_mov_b32_e32 v36, v35
	s_waitcnt vmcnt(9)
	v_pk_add_f32 v[10:11], v[42:43], 1.0 op_sel_hi:[1,0]
	v_pk_add_f32 v[12:13], v[40:41], 1.0 op_sel_hi:[1,0]
	v_pk_mul_f32 v[10:11], v[4:5], v[10:11]
	v_pk_mul_f32 v[12:13], v[2:3], v[12:13]
	v_cvt_pk_f16_f32 v11, v10, v11
	v_cvt_pk_f16_f32 v10, v12, v13
	s_waitcnt vmcnt(8)
	v_cvt_pk_f16_f32 v13, v46, v47
	v_cvt_pk_f16_f32 v12, v44, v45
	ds_write2st64_b64 v228, v[8:9], v[12:13] offset0:96 offset1:104
	v_mov_b32_e32 v37, v35
	s_waitcnt vmcnt(7)
	v_pk_add_f32 v[8:9], v[50:51], 1.0 op_sel_hi:[1,0]
	v_pk_add_f32 v[12:13], v[48:49], 1.0 op_sel_hi:[1,0]
	v_pk_mul_f32 v[8:9], v[4:5], v[8:9]
	v_pk_mul_f32 v[12:13], v[2:3], v[12:13]
	v_cvt_pk_f16_f32 v9, v8, v9
	v_cvt_pk_f16_f32 v8, v12, v13
	ds_write2st64_b64 v228, v[10:11], v[8:9] offset0:32 offset1:40
	s_waitcnt vmcnt(6)
; #define LAS __attribute__((address_space(3)))
; __device__ __forceinline__ u32x2 f32x4_to_h4(f32x4 v) { return __builtin_bit_cast(u32x2, __builtin_convertvector(v, f16x4)); }
; template <bool COMBINE, bool SRC_F32>
; __device__ __forceinline__ void norm_phase(LAS unsigned char* lds, const void* src_lat, const void* src_ctx, _Float16* xw_ctx, const float* part, int nrows, const float* g, const float* modl, int shift_idx, int scale_idx, bf16* HN, int tid, int lane, int wave) {
;     ...
;         for (int r = 0; r < 9; ++r) { *(LAS u32x2*)(Gs + r * D + 4 * tid) = f32x4_to_h4(gg * (1.0f + s1[r])); *(LAS u32x2*)(Ss + r * D + 4 * tid) = f32x4_to_h4(s0[r]); }
;     }
;     f32x4 v[8], nv[8];
;     ...
;     if (gw < nrows) NORM_LOAD(v, gw);
	v_cvt_pk_f16_f32 v9, v54, v55
	v_cvt_pk_f16_f32 v8, v52, v53
	v_mov_b32_e32 v38, v35
	s_waitcnt vmcnt(5)
	v_pk_add_f32 v[10:11], v[58:59], 1.0 op_sel_hi:[1,0]
	v_pk_add_f32 v[12:13], v[56:57], 1.0 op_sel_hi:[1,0]
	v_pk_mul_f32 v[10:11], v[4:5], v[10:11]
	v_pk_mul_f32 v[12:13], v[2:3], v[12:13]
	v_cvt_pk_f16_f32 v11, v10, v11
	v_cvt_pk_f16_f32 v10, v12, v13
	s_waitcnt vmcnt(4)
	v_cvt_pk_f16_f32 v13, v62, v63
	v_cvt_pk_f16_f32 v12, v60, v61
	ds_write2st64_b64 v228, v[8:9], v[12:13] offset0:112 offset1:120
	s_waitcnt vmcnt(3)
	v_pk_add_f32 v[8:9], v[66:67], 1.0 op_sel_hi:[1,0]
	v_pk_add_f32 v[12:13], v[64:65], 1.0 op_sel_hi:[1,0]
	v_pk_mul_f32 v[8:9], v[4:5], v[8:9]
	v_pk_mul_f32 v[12:13], v[2:3], v[12:13]
	v_cvt_pk_f16_f32 v9, v8, v9
	v_cvt_pk_f16_f32 v8, v12, v13
	ds_write2st64_b64 v228, v[10:11], v[8:9] offset0:48 offset1:56
	s_waitcnt vmcnt(1)
	v_pk_add_f32 v[10:11], v[74:75], 1.0 op_sel_hi:[1,0]
	v_pk_add_f32 v[12:13], v[72:73], 1.0 op_sel_hi:[1,0]
	v_pk_mul_f32 v[4:5], v[4:5], v[10:11]
	v_pk_mul_f32 v[2:3], v[2:3], v[12:13]
	v_cvt_pk_f16_f32 v9, v70, v71
	v_cvt_pk_f16_f32 v8, v68, v69
	v_cvt_pk_f16_f32 v5, v4, v5
	v_cvt_pk_f16_f32 v4, v2, v3
	s_waitcnt vmcnt(0)
	v_cvt_pk_f16_f32 v3, v78, v79
	v_cvt_pk_f16_f32 v2, v76, v77
	ds_write2st64_b64 v34, v[8:9], v[2:3] offset0:56 offset1:64
	v_mov_b32_e32 v34, v35
	v_mov_b32_e32 v39, v35
	v_mov_b32_e32 v40, v35
	v_mov_b32_e32 v41, v35
	v_mov_b32_e32 v42, v35
	v_mov_b32_e32 v43, v35
	v_mov_b32_e32 v44, v35
	v_mov_b32_e32 v45, v35
	v_mov_b32_e32 v46, v35
	v_mov_b32_e32 v47, v35
	v_mov_b32_e32 v48, v35
	v_mov_b32_e32 v49, v35
	v_mov_b32_e32 v50, v35
	v_mov_b32_e32 v51, v35
	v_mov_b32_e32 v52, v35
	v_mov_b32_e32 v53, v35
	v_mov_b32_e32 v54, v35
	v_mov_b32_e32 v55, v35
	v_mov_b32_e32 v56, v35
	v_mov_b32_e32 v57, v35
	v_mov_b32_e32 v58, v35
	v_mov_b32_e32 v59, v35
	v_mov_b32_e32 v60, v35
	v_mov_b32_e32 v61, v35
	v_mov_b32_e32 v62, v35
	v_mov_b32_e32 v63, v35
	v_mov_b32_e32 v64, v35
	v_mov_b32_e32 v65, v35
	v_readlane_b32 s13, v253, 15
	v_readlane_b32 s14, v253, 16
	v_readlane_b32 s15, v253, 17
	v_readlane_b32 s16, v253, 18
	v_readlane_b32 s17, v253, 19
	v_readlane_b32 s18, v253, 20
	v_readlane_b32 s19, v253, 21
	v_readlane_b32 s22, v253, 24
	v_readlane_b32 s23, v253, 25
	ds_write2st64_b64 v228, v[4:5], v[6:7] offset0:64 offset1:72
	s_cbranch_scc1 .LBB0_464
	s_ashr_i32 s1, s0, 31
	s_add_i32 s10, s0, 0xffffc000
	s_cmpk_lt_i32 s0, 0x4000
	s_cselect_b64 s[8:9], -1, 0
	s_and_b64 vcc, s[8:9], exec
	v_readlane_b32 s8, v253, 52
	v_readlane_b32 s9, v253, 53
	s_cselect_b32 s12, s9, s5
	s_cselect_b32 s13, s8, s4
	s_cselect_b32 s9, s1, 0
	s_cselect_b32 s8, s0, s10
	s_lshl_b64 s[10:11], s[8:9], 12
	s_add_u32 s10, s13, s10
	s_addc_u32 s11, s12, s11
	v_lshlrev_b32_e32 v14, 4, v1
	global_load_dwordx4 v[2:5], v14, s[10:11] nt
	global_load_dwordx4 v[6:9], v14, s[10:11] offset:1024 nt
	global_load_dwordx4 v[10:13], v14, s[10:11] offset:2048 nt
	s_nop 0
	global_load_dwordx4 v[14:17], v14, s[10:11] offset:3072 nt
	s_waitcnt vmcnt(3)
	v_cvt_f32_f16_e32 v36, v3
	v_cvt_f32_f16_e32 v34, v2
	v_cvt_f32_f16_sdwa v37, v3 dst_sel:DWORD dst_unused:UNUSED_PAD src0_sel:WORD_1
	v_cvt_f32_f16_sdwa v35, v2 dst_sel:DWORD dst_unused:UNUSED_PAD src0_sel:WORD_1
	v_cvt_f32_f16_e32 v40, v5
	v_cvt_f32_f16_e32 v38, v4
	v_cvt_f32_f16_sdwa v41, v5 dst_sel:DWORD dst_unused:UNUSED_PAD src0_sel:WORD_1
	v_cvt_f32_f16_sdwa v39, v4 dst_sel:DWORD dst_unused:UNUSED_PAD src0_sel:WORD_1
	s_waitcnt vmcnt(2)
	v_cvt_f32_f16_e32 v44, v7
	v_cvt_f32_f16_e32 v42, v6
	v_cvt_f32_f16_sdwa v45, v7 dst_sel:DWORD dst_unused:UNUSED_PAD src0_sel:WORD_1
	v_cvt_f32_f16_sdwa v43, v6 dst_sel:DWORD dst_unused:UNUSED_PAD src0_sel:WORD_1
	v_cvt_f32_f16_e32 v48, v9
	v_cvt_f32_f16_e32 v46, v8
	v_cvt_f32_f16_sdwa v49, v9 dst_sel:DWORD dst_unused:UNUSED_PAD src0_sel:WORD_1
	v_cvt_f32_f16_sdwa v47, v8 dst_sel:DWORD dst_unused:UNUSED_PAD src0_sel:WORD_1
	s_waitcnt vmcnt(1)
	v_cvt_f32_f16_e32 v52, v11
	v_cvt_f32_f16_e32 v50, v10
	v_cvt_f32_f16_sdwa v53, v11 dst_sel:DWORD dst_unused:UNUSED_PAD src0_sel:WORD_1
	v_cvt_f32_f16_sdwa v51, v10 dst_sel:DWORD dst_unused:UNUSED_PAD src0_sel:WORD_1
	v_cvt_f32_f16_e32 v56, v13
	v_cvt_f32_f16_e32 v54, v12
	v_cvt_f32_f16_sdwa v57, v13 dst_sel:DWORD dst_unused:UNUSED_PAD src0_sel:WORD_1
	v_cvt_f32_f16_sdwa v55, v12 dst_sel:DWORD dst_unused:UNUSED_PAD src0_sel:WORD_1
	s_waitcnt vmcnt(0)
	v_cvt_f32_f16_e32 v60, v15
	v_cvt_f32_f16_e32 v58, v14
	v_cvt_f32_f16_sdwa v61, v15 dst_sel:DWORD dst_unused:UNUSED_PAD src0_sel:WORD_1
	v_cvt_f32_f16_sdwa v59, v14 dst_sel:DWORD dst_unused:UNUSED_PAD src0_sel:WORD_1
	v_cvt_f32_f16_e32 v64, v17
	v_cvt_f32_f16_e32 v62, v16
	v_cvt_f32_f16_sdwa v65, v17 dst_sel:DWORD dst_unused:UNUSED_PAD src0_sel:WORD_1
	v_cvt_f32_f16_sdwa v63, v16 dst_sel:DWORD dst_unused:UNUSED_PAD src0_sel:WORD_1
	s_cbranch_vccnz .LBB0_464
; template <bool COMBINE, bool SRC_F32>
; __device__ __forceinline__ void norm_phase(LAS unsigned char* lds, const void* src_lat, const void* src_ctx, _Float16* xw_ctx, const float* part, int nrows, const float* g, const float* modl, int shift_idx, int scale_idx, bf16* HN, int tid, int lane, int wave) {
;     ...
;     if (gw < nrows) NORM_LOAD(v, gw);
	s_lshl_b64 s[8:9], s[8:9], 11
	s_lshl_b64 s[8:9], s[8:9], 2
	v_readlane_b32 s1, v253, 54
	s_add_u32 s8, s1, s8
	v_readlane_b32 s1, v253, 56
	v_lshlrev_b32_e32 v2, 3, v1
	s_addc_u32 s9, s1, s9
	v_lshlrev_b32_e32 v102, 2, v2
	s_add_u32 s10, s8, 0x1000000
	s_addc_u32 s11, s9, 0
	v_or_b32_e32 v110, 0x800, v102
	v_or_b32_e32 v126, 0x1800, v102
	global_load_dwordx4 v[2:5], v102, s[8:9] offset:16 nt
	global_load_dwordx4 v[6:9], v102, s[8:9] nt
	global_load_dwordx4 v[10:13], v102, s[8:9] offset:2064 nt
	global_load_dwordx4 v[14:17], v102, s[8:9] offset:2048 nt
	global_load_dwordx4 v[18:21], v102, s[10:11] offset:16 nt
	global_load_dwordx4 v[22:25], v102, s[10:11] nt
	v_or_b32_e32 v118, 0x1000, v102
	global_load_dwordx4 v[26:29], v110, s[10:11] offset:16 nt
	global_load_dwordx4 v[30:33], v110, s[10:11] nt
	global_load_dwordx4 v[66:69], v118, s[8:9] offset:16 nt
	global_load_dwordx4 v[70:73], v118, s[8:9] nt
	global_load_dwordx4 v[74:77], v118, s[10:11] offset:16 nt
	global_load_dwordx4 v[78:81], v118, s[10:11] nt
	global_load_dwordx4 v[82:85], v126, s[8:9] offset:16 nt
	global_load_dwordx4 v[86:89], v126, s[8:9] nt
	global_load_dwordx4 v[90:93], v126, s[10:11] nt
	global_load_dwordx4 v[94:97], v126, s[10:11] offset:16 nt
	s_add_u32 s8, s8, 0x2000000
	s_addc_u32 s9, s9, 0
	global_load_dwordx4 v[98:101], v102, s[8:9] nt
	s_nop 0
	global_load_dwordx4 v[102:105], v102, s[8:9] offset:16 nt
	s_nop 0
	global_load_dwordx4 v[106:109], v110, s[8:9] nt
	s_nop 0
	global_load_dwordx4 v[110:113], v110, s[8:9] offset:16 nt
	s_nop 0
	global_load_dwordx4 v[114:117], v118, s[8:9] nt
	s_nop 0
	global_load_dwordx4 v[118:121], v118, s[8:9] offset:16 nt
	s_nop 0
	global_load_dwordx4 v[122:125], v126, s[8:9] nt
	s_nop 0
	global_load_dwordx4 v[126:129], v126, s[8:9] offset:16 nt
	s_waitcnt vmcnt(17)
	v_pk_add_f32 v[12:13], v[12:13], v[28:29]
	v_pk_add_f32 v[4:5], v[4:5], v[20:21]
	v_pk_add_f32 v[8:9], v[8:9], v[24:25]
	v_pk_add_f32 v[6:7], v[6:7], v[22:23]
	v_pk_add_f32 v[2:3], v[2:3], v[18:19]
	s_waitcnt vmcnt(16)
	v_pk_add_f32 v[16:17], v[16:17], v[32:33]
	v_pk_add_f32 v[14:15], v[14:15], v[30:31]
	v_pk_add_f32 v[10:11], v[10:11], v[26:27]
	s_waitcnt vmcnt(12)
	v_pk_add_f32 v[18:19], v[72:73], v[80:81]
	v_pk_add_f32 v[20:21], v[70:71], v[78:79]
	v_pk_add_f32 v[22:23], v[68:69], v[76:77]
	v_pk_add_f32 v[24:25], v[66:67], v[74:75]
	s_waitcnt vmcnt(9)
	v_pk_add_f32 v[26:27], v[88:89], v[92:93]
	v_pk_add_f32 v[28:29], v[86:87], v[90:91]
	s_waitcnt vmcnt(8)
	v_pk_add_f32 v[30:31], v[84:85], v[96:97]
	v_pk_add_f32 v[32:33], v[82:83], v[94:95]
	s_waitcnt vmcnt(7)
	v_pk_add_f32 v[8:9], v[8:9], v[100:101]
	v_pk_add_f32 v[6:7], v[6:7], v[98:99]
	s_waitcnt vmcnt(6)
	v_pk_add_f32 v[4:5], v[4:5], v[104:105]
	v_pk_add_f32 v[2:3], v[2:3], v[102:103]
	s_waitcnt vmcnt(5)
	v_pk_add_f32 v[16:17], v[16:17], v[108:109]
	v_pk_add_f32 v[14:15], v[14:15], v[106:107]
	s_waitcnt vmcnt(4)
	v_pk_add_f32 v[12:13], v[12:13], v[112:113]
	v_pk_add_f32 v[10:11], v[10:11], v[110:111]
	s_waitcnt vmcnt(3)
	v_pk_add_f32 v[18:19], v[18:19], v[116:117]
	v_pk_add_f32 v[20:21], v[20:21], v[114:115]
	s_waitcnt vmcnt(2)
	v_pk_add_f32 v[22:23], v[22:23], v[120:121]
	v_pk_add_f32 v[24:25], v[24:25], v[118:119]
	s_waitcnt vmcnt(1)
	v_pk_add_f32 v[26:27], v[26:27], v[124:125]
	v_pk_add_f32 v[28:29], v[28:29], v[122:123]
	s_waitcnt vmcnt(0)
	v_pk_add_f32 v[30:31], v[30:31], v[128:129]
	v_pk_add_f32 v[32:33], v[32:33], v[126:127]
	v_pk_add_f32 v[36:37], v[8:9], v[36:37]
	v_pk_add_f32 v[34:35], v[6:7], v[34:35]
	v_pk_add_f32 v[40:41], v[4:5], v[40:41]
	v_pk_add_f32 v[38:39], v[2:3], v[38:39]
	v_pk_add_f32 v[44:45], v[16:17], v[44:45]
	v_pk_add_f32 v[42:43], v[14:15], v[42:43]
	v_pk_add_f32 v[48:49], v[12:13], v[48:49]
	v_pk_add_f32 v[46:47], v[10:11], v[46:47]
	v_pk_add_f32 v[52:53], v[18:19], v[52:53]
	v_pk_add_f32 v[50:51], v[20:21], v[50:51]
	v_pk_add_f32 v[56:57], v[22:23], v[56:57]
	v_pk_add_f32 v[54:55], v[24:25], v[54:55]
	v_pk_add_f32 v[60:61], v[26:27], v[60:61]
	v_pk_add_f32 v[58:59], v[28:29], v[58:59]
	v_pk_add_f32 v[64:65], v[30:31], v[64:65]
	v_pk_add_f32 v[62:63], v[32:33], v[62:63]

; __device__ __forceinline__ void lds_barrier() { asm volatile("s_waitcnt lgkmcnt(0)" ::: "memory"); __builtin_amdgcn_s_barrier(); asm volatile("" ::: "memory"); }
; template <bool COMBINE, bool SRC_F32>
; __device__ __forceinline__ void norm_phase(LAS unsigned char* lds, const void* src_lat, const void* src_ctx, _Float16* xw_ctx, const float* part, int nrows, const float* g, const float* modl, int shift_idx, int scale_idx, bf16* HN, int tid, int lane, int wave) {
;     ...
;     if (gw < nrows) NORM_LOAD(v, gw);
;     lds_barrier();
;     for (int row = gw; row < nrows; row += NGW) {
;         if (row + NGW < nrows) NORM_LOAD(nv, row + NGW);
.LBB0_467:
	s_add_i32 s14, s6, s8
	s_add_i32 s0, s14, 0x4000
	s_cmpk_gt_i32 s0, 0x47ff
	s_cselect_b64 s[12:13], -1, 0
	s_and_b64 vcc, exec, s[12:13]
	s_cbranch_vccnz .LBB0_470
	s_ashr_i32 s1, s0, 31
	s_cmpk_lt_i32 s0, 0x4000
	s_cselect_b64 s[16:17], -1, 0
	s_and_b64 vcc, s[16:17], exec
	v_readlane_b32 s16, v253, 52
	v_readlane_b32 s17, v253, 53
	s_cselect_b32 s1, s1, 0
	s_cselect_b32 s0, s0, s14
	s_cselect_b32 s15, s17, s5
	s_cselect_b32 s18, s16, s4
	s_lshl_b64 s[16:17], s[0:1], 12
	s_add_u32 s16, s18, s16
	s_addc_u32 s17, s15, s17
	v_lshlrev_b32_e32 v2, 1, v66
	global_load_dwordx4 v[8:11], v2, s[16:17] nt
	global_load_dwordx4 v[16:19], v2, s[16:17] offset:1024 nt
	global_load_dwordx4 v[24:27], v2, s[16:17] offset:2048 nt
	global_load_dwordx4 v[80:83], v2, s[16:17] offset:3072 nt
	s_waitcnt vmcnt(3)
	v_cvt_f32_f16_e32 v4, v9
	v_cvt_f32_f16_e32 v2, v8
	v_cvt_f32_f16_sdwa v5, v9 dst_sel:DWORD dst_unused:UNUSED_PAD src0_sel:WORD_1
	v_cvt_f32_f16_sdwa v3, v8 dst_sel:DWORD dst_unused:UNUSED_PAD src0_sel:WORD_1
	v_cvt_f32_f16_e32 v8, v11
	v_cvt_f32_f16_e32 v6, v10
	v_cvt_f32_f16_sdwa v9, v11 dst_sel:DWORD dst_unused:UNUSED_PAD src0_sel:WORD_1
	v_cvt_f32_f16_sdwa v7, v10 dst_sel:DWORD dst_unused:UNUSED_PAD src0_sel:WORD_1
	s_waitcnt vmcnt(2)
	v_cvt_f32_f16_e32 v12, v17
	v_cvt_f32_f16_e32 v10, v16
	v_cvt_f32_f16_sdwa v13, v17 dst_sel:DWORD dst_unused:UNUSED_PAD src0_sel:WORD_1
	v_cvt_f32_f16_sdwa v11, v16 dst_sel:DWORD dst_unused:UNUSED_PAD src0_sel:WORD_1
	v_cvt_f32_f16_e32 v16, v19
	v_cvt_f32_f16_e32 v14, v18
	v_cvt_f32_f16_sdwa v17, v19 dst_sel:DWORD dst_unused:UNUSED_PAD src0_sel:WORD_1
	v_cvt_f32_f16_sdwa v15, v18 dst_sel:DWORD dst_unused:UNUSED_PAD src0_sel:WORD_1
	s_waitcnt vmcnt(1)
	v_cvt_f32_f16_e32 v20, v25
	v_cvt_f32_f16_e32 v18, v24
	v_cvt_f32_f16_sdwa v21, v25 dst_sel:DWORD dst_unused:UNUSED_PAD src0_sel:WORD_1
	v_cvt_f32_f16_sdwa v19, v24 dst_sel:DWORD dst_unused:UNUSED_PAD src0_sel:WORD_1
	v_cvt_f32_f16_e32 v24, v27
	v_cvt_f32_f16_e32 v22, v26
	v_cvt_f32_f16_sdwa v25, v27 dst_sel:DWORD dst_unused:UNUSED_PAD src0_sel:WORD_1
	v_cvt_f32_f16_sdwa v23, v26 dst_sel:DWORD dst_unused:UNUSED_PAD src0_sel:WORD_1
	s_waitcnt vmcnt(0)
	v_cvt_f32_f16_e32 v28, v81
	v_cvt_f32_f16_e32 v26, v80
	v_cvt_f32_f16_sdwa v29, v81 dst_sel:DWORD dst_unused:UNUSED_PAD src0_sel:WORD_1
	v_cvt_f32_f16_sdwa v27, v80 dst_sel:DWORD dst_unused:UNUSED_PAD src0_sel:WORD_1
	v_cvt_f32_f16_e32 v32, v83
	v_cvt_f32_f16_e32 v30, v82
	v_cvt_f32_f16_sdwa v33, v83 dst_sel:DWORD dst_unused:UNUSED_PAD src0_sel:WORD_1
	v_cvt_f32_f16_sdwa v31, v82 dst_sel:DWORD dst_unused:UNUSED_PAD src0_sel:WORD_1
	s_cbranch_vccnz .LBB0_470
	s_lshl_b64 s[0:1], s[0:1], 11
	s_lshl_b64 s[0:1], s[0:1], 2
	v_readlane_b32 s15, v253, 54
	s_add_u32 s0, s15, s0
	v_readlane_b32 s15, v253, 56
	s_addc_u32 s1, s15, s1
	s_add_u32 s16, s0, 0x1000000
	v_lshlrev_b32_e32 v72, 2, v66
	s_addc_u32 s17, s1, 0
	global_load_dwordx4 v[80:83], v72, s[0:1] offset:16 nt
	global_load_dwordx4 v[84:87], v72, s[0:1] nt
	global_load_dwordx4 v[88:91], v72, s[16:17] nt
	global_load_dwordx4 v[92:95], v72, s[16:17] offset:16 nt
	global_load_dwordx4 v[96:99], v72, s[0:1] offset:2064 nt
	global_load_dwordx4 v[100:103], v72, s[0:1] offset:2048 nt
	global_load_dwordx4 v[104:107], v75, s[16:17] nt
	global_load_dwordx4 v[108:111], v75, s[16:17] offset:16 nt
	global_load_dwordx4 v[112:115], v73, s[0:1] offset:16 nt
	global_load_dwordx4 v[116:119], v73, s[0:1] nt
	global_load_dwordx4 v[120:123], v73, s[16:17] nt
	global_load_dwordx4 v[124:127], v73, s[16:17] offset:16 nt
	global_load_dwordx4 v[128:131], v74, s[0:1] offset:16 nt
	global_load_dwordx4 v[132:135], v74, s[0:1] nt
	global_load_dwordx4 v[136:139], v74, s[16:17] nt
	global_load_dwordx4 v[140:143], v74, s[16:17] offset:16 nt
	s_add_u32 s0, s0, 0x2000000
	s_addc_u32 s1, s1, 0
	global_load_dwordx4 v[144:147], v72, s[0:1] nt
	global_load_dwordx4 v[148:151], v72, s[0:1] offset:16 nt
	global_load_dwordx4 v[152:155], v75, s[0:1] nt
	global_load_dwordx4 v[156:159], v75, s[0:1] offset:16 nt
	global_load_dwordx4 v[160:163], v73, s[0:1] nt
	global_load_dwordx4 v[164:167], v73, s[0:1] offset:16 nt
	global_load_dwordx4 v[168:171], v74, s[0:1] nt
	global_load_dwordx4 v[172:175], v74, s[0:1] offset:16 nt
	s_waitcnt vmcnt(20)
	v_pk_add_f32 v[82:83], v[82:83], v[94:95]
	v_pk_add_f32 v[86:87], v[86:87], v[90:91]
	v_pk_add_f32 v[84:85], v[84:85], v[88:89]
	v_pk_add_f32 v[80:81], v[80:81], v[92:93]
	s_waitcnt vmcnt(17)
	v_pk_add_f32 v[88:89], v[102:103], v[106:107]
	v_pk_add_f32 v[90:91], v[100:101], v[104:105]
	s_waitcnt vmcnt(16)
	v_pk_add_f32 v[92:93], v[98:99], v[110:111]
	v_pk_add_f32 v[94:95], v[96:97], v[108:109]
	s_waitcnt vmcnt(13)
	v_pk_add_f32 v[96:97], v[118:119], v[122:123]
	v_pk_add_f32 v[98:99], v[116:117], v[120:121]
	s_waitcnt vmcnt(12)
	v_pk_add_f32 v[100:101], v[114:115], v[126:127]
	v_pk_add_f32 v[102:103], v[112:113], v[124:125]
	s_waitcnt vmcnt(9)
	v_pk_add_f32 v[104:105], v[134:135], v[138:139]
	v_pk_add_f32 v[106:107], v[132:133], v[136:137]
	s_waitcnt vmcnt(8)
	v_pk_add_f32 v[108:109], v[130:131], v[142:143]
	v_pk_add_f32 v[110:111], v[128:129], v[140:141]
	s_waitcnt vmcnt(7)
	v_pk_add_f32 v[86:87], v[86:87], v[146:147]
	v_pk_add_f32 v[84:85], v[84:85], v[144:145]
	s_waitcnt vmcnt(6)
	v_pk_add_f32 v[82:83], v[82:83], v[150:151]
	v_pk_add_f32 v[80:81], v[80:81], v[148:149]
	s_waitcnt vmcnt(5)
	v_pk_add_f32 v[88:89], v[88:89], v[154:155]
	v_pk_add_f32 v[90:91], v[90:91], v[152:153]
	s_waitcnt vmcnt(4)
	v_pk_add_f32 v[92:93], v[92:93], v[158:159]
	v_pk_add_f32 v[94:95], v[94:95], v[156:157]
	s_waitcnt vmcnt(3)
	v_pk_add_f32 v[96:97], v[96:97], v[162:163]
	v_pk_add_f32 v[98:99], v[98:99], v[160:161]
	s_waitcnt vmcnt(2)
	v_pk_add_f32 v[100:101], v[100:101], v[166:167]
	v_pk_add_f32 v[102:103], v[102:103], v[164:165]
	s_waitcnt vmcnt(1)
	v_pk_add_f32 v[104:105], v[104:105], v[170:171]
	v_pk_add_f32 v[106:107], v[106:107], v[168:169]
	s_waitcnt vmcnt(0)
	v_pk_add_f32 v[108:109], v[108:109], v[174:175]
	v_pk_add_f32 v[110:111], v[110:111], v[172:173]
	v_pk_add_f32 v[4:5], v[86:87], v[4:5]
	v_pk_add_f32 v[2:3], v[84:85], v[2:3]
	v_pk_add_f32 v[8:9], v[82:83], v[8:9]
	v_pk_add_f32 v[6:7], v[80:81], v[6:7]
	v_pk_add_f32 v[12:13], v[88:89], v[12:13]
	v_pk_add_f32 v[10:11], v[90:91], v[10:11]
	v_pk_add_f32 v[16:17], v[92:93], v[16:17]
	v_pk_add_f32 v[14:15], v[94:95], v[14:15]
	v_pk_add_f32 v[20:21], v[96:97], v[20:21]
	v_pk_add_f32 v[18:19], v[98:99], v[18:19]
	v_pk_add_f32 v[24:25], v[100:101], v[24:25]
	v_pk_add_f32 v[22:23], v[102:103], v[22:23]
	v_pk_add_f32 v[28:29], v[104:105], v[28:29]
	v_pk_add_f32 v[26:27], v[106:107], v[26:27]
	v_pk_add_f32 v[32:33], v[108:109], v[32:33]
	v_pk_add_f32 v[30:31], v[110:111], v[30:31]

; #define LAS __attribute__((address_space(3)))
; __device__ __forceinline__ u32x2 f32x4_to_h4(f32x4 v) { return __builtin_bit_cast(u32x2, __builtin_convertvector(v, f16x4)); }
; template <bool COMBINE, bool SRC_F32>
; __device__ __forceinline__ void norm_phase(LAS unsigned char* lds, const void* src_lat, const void* src_ctx, _Float16* xw_ctx, const float* part, int nrows, const float* g, const float* modl, int shift_idx, int scale_idx, bf16* HN, int tid, int lane, int wave) {
;     const int gw = blockIdx.x * 8 + wave, NGW = gridDim.x * 8;
;     LAS _Float16* Gs = (LAS _Float16*)lds;
;     LAS _Float16* Ss = Gs + 9 * D;
;     {
;         const f32x4 gg = *(const f32x4*)(g + 4 * tid);
;         f32x4 s1[9], s0[9];
; #pragma unroll
;         for (int r = 0; r < 9; ++r) { s1[r] = *(const f32x4*)(modl + (size_t)r * DMODW + scale_idx * D + 4 * tid); s0[r] = *(const f32x4*)(modl + (size_t)r * DMODW + shift_idx * D + 4 * tid); }
; #pragma unroll
;         for (int r = 0; r < 9; ++r) { *(LAS u32x2*)(Gs + r * D + 4 * tid) = f32x4_to_h4(gg * (1.0f + s1[r])); *(LAS u32x2*)(Ss + r * D + 4 * tid) = f32x4_to_h4(s0[r]); }
;     }
.LBB0_1022:
	s_cmp_lt_i32 s90, 9
	s_cselect_b64 s[2:3], -1, 0
	s_and_b64 s[0:1], s[2:3], s[0:1]
	s_andn2_b64 vcc, exec, s[0:1]
	s_cbranch_vccnz .LBB0_1035
	v_readlane_b32 s8, v253, 10
	s_waitcnt vmcnt(0)
	v_lshlrev_b32_e32 v34, 4, v0
	v_mov_b32_e32 v35, 0
	v_readlane_b32 s20, v253, 22
	v_readlane_b32 s21, v253, 23
	v_lshl_add_u64 v[76:77], s[88:89], 0, v[34:35]
	s_add_u32 s4, s88, 0x18400000
	v_lshl_add_u64 v[2:3], s[20:21], 0, v[34:35]
	v_add_co_u32_e32 v2, vcc, 0x4000, v2
	s_addc_u32 s5, s89, 0
	s_nop 0
	v_addc_co_u32_e32 v3, vcc, 0, v3, vcc
	v_add_co_u32_e32 v6, vcc, 0x10e000, v76
	global_load_dwordx4 v[2:5], v[2:3], off
	s_nop 0
	v_addc_co_u32_e32 v7, vcc, 0, v77, vcc
	v_add_co_u32_e32 v10, vcc, 0x10c000, v76
	s_lshl_b32 s0, s86, 3
	s_nop 0
	v_addc_co_u32_e32 v11, vcc, 0, v77, vcc
	v_add_co_u32_e32 v14, vcc, 0x120000, v76
	global_load_dwordx4 v[6:9], v[6:7], off
	s_nop 0
	global_load_dwordx4 v[10:13], v[10:11], off
	v_addc_co_u32_e32 v15, vcc, 0, v77, vcc
	v_add_co_u32_e32 v18, vcc, 0x11e000, v76
	v_readlane_b32 s1, v253, 31
	s_nop 0
	v_addc_co_u32_e32 v19, vcc, 0, v77, vcc
	v_add_co_u32_e32 v22, vcc, 0x132000, v76
	global_load_dwordx4 v[14:17], v[14:15], off
	s_nop 0
	global_load_dwordx4 v[18:21], v[18:19], off
	v_addc_co_u32_e32 v23, vcc, 0, v77, vcc
	v_add_co_u32_e32 v26, vcc, 0x130000, v76
	s_add_i32 s0, s1, s0
	s_nop 0
	v_addc_co_u32_e32 v27, vcc, 0, v77, vcc
	v_add_co_u32_e32 v30, vcc, 0x144000, v76
	global_load_dwordx4 v[22:25], v[22:23], off
	s_nop 0
	global_load_dwordx4 v[26:29], v[26:27], off
	v_addc_co_u32_e32 v31, vcc, 0, v77, vcc
	v_add_co_u32_e32 v36, vcc, 0x142000, v76
	v_add_u32_e32 v34, 0x9000, v228
	s_nop 0
	v_addc_co_u32_e32 v37, vcc, 0, v77, vcc
	v_add_co_u32_e32 v40, vcc, 0x156000, v76
	global_load_dwordx4 v[30:33], v[30:31], off
	s_nop 0
	global_load_dwordx4 v[36:39], v[36:37], off
	v_addc_co_u32_e32 v41, vcc, 0, v77, vcc
	v_add_co_u32_e32 v44, vcc, 0x154000, v76
	s_cmpk_lt_i32 s0, 0x4800
	s_nop 0
	v_addc_co_u32_e32 v45, vcc, 0, v77, vcc
	v_add_co_u32_e32 v48, vcc, 0x168000, v76
	global_load_dwordx4 v[40:43], v[40:41], off
	s_nop 0
	global_load_dwordx4 v[44:47], v[44:45], off
	v_addc_co_u32_e32 v49, vcc, 0, v77, vcc
	v_add_co_u32_e32 v52, vcc, 0x166000, v76
	s_cselect_b64 s[6:7], -1, 0
	s_nop 0
	v_addc_co_u32_e32 v53, vcc, 0, v77, vcc
	v_add_co_u32_e32 v56, vcc, 0x17a000, v76
	global_load_dwordx4 v[48:51], v[48:49], off
	s_nop 0
	global_load_dwordx4 v[52:55], v[52:53], off
	v_addc_co_u32_e32 v57, vcc, 0, v77, vcc
	v_add_co_u32_e32 v60, vcc, 0x178000, v76
	s_cmpk_gt_i32 s0, 0x47ff
	s_nop 0
	v_addc_co_u32_e32 v61, vcc, 0, v77, vcc
	v_add_co_u32_e32 v64, vcc, 0x18c000, v76
	global_load_dwordx4 v[56:59], v[56:57], off
	s_nop 0
	global_load_dwordx4 v[60:63], v[60:61], off
	v_addc_co_u32_e32 v65, vcc, 0, v77, vcc
	v_add_co_u32_e32 v68, vcc, 0x18a000, v76
	global_load_dwordx4 v[64:67], v[64:65], off
	s_nop 0
	v_addc_co_u32_e32 v69, vcc, 0, v77, vcc
	v_add_co_u32_e32 v72, vcc, 0x19e000, v76
	global_load_dwordx4 v[68:71], v[68:69], off
	s_nop 0
	v_addc_co_u32_e32 v73, vcc, 0, v77, vcc
	global_load_dwordx4 v[72:75], v[72:73], off
	v_add_co_u32_e32 v76, vcc, 0x19c000, v76
	v_readlane_b32 s9, v253, 11
	s_nop 0
	v_addc_co_u32_e32 v77, vcc, 0, v77, vcc
	global_load_dwordx4 v[76:79], v[76:77], off
	s_waitcnt vmcnt(17)
	v_pk_add_f32 v[8:9], v[8:9], 1.0 op_sel_hi:[1,0]
	v_pk_add_f32 v[6:7], v[6:7], 1.0 op_sel_hi:[1,0]
	v_pk_mul_f32 v[8:9], v[4:5], v[8:9]
	v_pk_mul_f32 v[6:7], v[2:3], v[6:7]
	v_cvt_pk_f16_f32 v9, v8, v9
	v_cvt_pk_f16_f32 v8, v6, v7
	s_waitcnt vmcnt(16)
	v_cvt_pk_f16_f32 v7, v12, v13
	v_cvt_pk_f16_f32 v6, v10, v11
	v_readlane_b32 s10, v253, 12
	s_waitcnt vmcnt(15)
	v_pk_add_f32 v[10:11], v[16:17], 1.0 op_sel_hi:[1,0]
	v_pk_add_f32 v[12:13], v[14:15], 1.0 op_sel_hi:[1,0]
	v_pk_mul_f32 v[10:11], v[4:5], v[10:11]
	v_pk_mul_f32 v[12:13], v[2:3], v[12:13]
	v_cvt_pk_f16_f32 v11, v10, v11
	v_cvt_pk_f16_f32 v10, v12, v13
	ds_write2st64_b64 v228, v[8:9], v[10:11] offset1:8
	s_waitcnt vmcnt(14)
	v_cvt_pk_f16_f32 v9, v20, v21
	v_cvt_pk_f16_f32 v8, v18, v19
	v_readlane_b32 s11, v253, 13
	s_waitcnt vmcnt(13)
	v_pk_add_f32 v[10:11], v[24:25], 1.0 op_sel_hi:[1,0]
	v_pk_add_f32 v[12:13], v[22:23], 1.0 op_sel_hi:[1,0]
	v_pk_mul_f32 v[10:11], v[4:5], v[10:11]
	v_pk_mul_f32 v[12:13], v[2:3], v[12:13]
	v_cvt_pk_f16_f32 v11, v10, v11
	v_cvt_pk_f16_f32 v10, v12, v13
	s_waitcnt vmcnt(12)
	v_cvt_pk_f16_f32 v13, v28, v29
	v_cvt_pk_f16_f32 v12, v26, v27
	ds_write2st64_b64 v228, v[8:9], v[12:13] offset0:80 offset1:88
	v_readlane_b32 s12, v253, 14
	s_waitcnt vmcnt(11)
	v_pk_add_f32 v[8:9], v[32:33], 1.0 op_sel_hi:[1,0]
	v_pk_add_f32 v[12:13], v[30:31], 1.0 op_sel_hi:[1,0]
	v_pk_mul_f32 v[8:9], v[4:5], v[8:9]
	v_pk_mul_f32 v[12:13], v[2:3], v[12:13]
	v_cvt_pk_f16_f32 v9, v8, v9
	v_cvt_pk_f16_f32 v8, v12, v13
	ds_write2st64_b64 v228, v[10:11], v[8:9] offset0:16 offset1:24
	s_waitcnt vmcnt(10)
	v_cvt_pk_f16_f32 v9, v38, v39
	v_cvt_pk_f16_f32 v8, v36, v37
	v_mov_b32_e32 v36, v35
	s_waitcnt vmcnt(9)
	v_pk_add_f32 v[10:11], v[42:43], 1.0 op_sel_hi:[1,0]
	v_pk_add_f32 v[12:13], v[40:41], 1.0 op_sel_hi:[1,0]
	v_pk_mul_f32 v[10:11], v[4:5], v[10:11]
	v_pk_mul_f32 v[12:13], v[2:3], v[12:13]
	v_cvt_pk_f16_f32 v11, v10, v11
	v_cvt_pk_f16_f32 v10, v12, v13
	s_waitcnt vmcnt(8)
	v_cvt_pk_f16_f32 v13, v46, v47
	v_cvt_pk_f16_f32 v12, v44, v45
	ds_write2st64_b64 v228, v[8:9], v[12:13] offset0:96 offset1:104
	v_mov_b32_e32 v37, v35
	s_waitcnt vmcnt(7)
	v_pk_add_f32 v[8:9], v[50:51], 1.0 op_sel_hi:[1,0]
	v_pk_add_f32 v[12:13], v[48:49], 1.0 op_sel_hi:[1,0]
	v_pk_mul_f32 v[8:9], v[4:5], v[8:9]
	v_pk_mul_f32 v[12:13], v[2:3], v[12:13]
	v_cvt_pk_f16_f32 v9, v8, v9
	v_cvt_pk_f16_f32 v8, v12, v13
	ds_write2st64_b64 v228, v[10:11], v[8:9] offset0:32 offset1:40
	s_waitcnt vmcnt(6)
; #define LAS __attribute__((address_space(3)))
; __device__ __forceinline__ u32x2 f32x4_to_h4(f32x4 v) { return __builtin_bit_cast(u32x2, __builtin_convertvector(v, f16x4)); }
; template <bool COMBINE, bool SRC_F32>
; __device__ __forceinline__ void norm_phase(LAS unsigned char* lds, const void* src_lat, const void* src_ctx, _Float16* xw_ctx, const float* part, int nrows, const float* g, const float* modl, int shift_idx, int scale_idx, bf16* HN, int tid, int lane, int wave) {
;     ...
;         for (int r = 0; r < 9; ++r) { *(LAS u32x2*)(Gs + r * D + 4 * tid) = f32x4_to_h4(gg * (1.0f + s1[r])); *(LAS u32x2*)(Ss + r * D + 4 * tid) = f32x4_to_h4(s0[r]); }
;     }
;     f32x4 v[8], nv[8];
;     ...
;     if (gw < nrows) NORM_LOAD(v, gw);
	v_cvt_pk_f16_f32 v9, v54, v55
	v_cvt_pk_f16_f32 v8, v52, v53
	v_mov_b32_e32 v38, v35
	s_waitcnt vmcnt(5)
	v_pk_add_f32 v[10:11], v[58:59], 1.0 op_sel_hi:[1,0]
	v_pk_add_f32 v[12:13], v[56:57], 1.0 op_sel_hi:[1,0]
	v_pk_mul_f32 v[10:11], v[4:5], v[10:11]
	v_pk_mul_f32 v[12:13], v[2:3], v[12:13]
	v_cvt_pk_f16_f32 v11, v10, v11
	v_cvt_pk_f16_f32 v10, v12, v13
	s_waitcnt vmcnt(4)
	v_cvt_pk_f16_f32 v13, v62, v63
	v_cvt_pk_f16_f32 v12, v60, v61
	ds_write2st64_b64 v228, v[8:9], v[12:13] offset0:112 offset1:120
	s_waitcnt vmcnt(3)
	v_pk_add_f32 v[8:9], v[66:67], 1.0 op_sel_hi:[1,0]
	v_pk_add_f32 v[12:13], v[64:65], 1.0 op_sel_hi:[1,0]
	v_pk_mul_f32 v[8:9], v[4:5], v[8:9]
	v_pk_mul_f32 v[12:13], v[2:3], v[12:13]
	v_cvt_pk_f16_f32 v9, v8, v9
	v_cvt_pk_f16_f32 v8, v12, v13
	ds_write2st64_b64 v228, v[10:11], v[8:9] offset0:48 offset1:56
	s_waitcnt vmcnt(1)
	v_pk_add_f32 v[10:11], v[74:75], 1.0 op_sel_hi:[1,0]
	v_pk_add_f32 v[12:13], v[72:73], 1.0 op_sel_hi:[1,0]
	v_pk_mul_f32 v[4:5], v[4:5], v[10:11]
	v_pk_mul_f32 v[2:3], v[2:3], v[12:13]
	v_cvt_pk_f16_f32 v9, v70, v71
	v_cvt_pk_f16_f32 v8, v68, v69
	v_cvt_pk_f16_f32 v5, v4, v5
	v_cvt_pk_f16_f32 v4, v2, v3
	s_waitcnt vmcnt(0)
	v_cvt_pk_f16_f32 v3, v78, v79
	v_cvt_pk_f16_f32 v2, v76, v77
	ds_write2st64_b64 v34, v[8:9], v[2:3] offset0:56 offset1:64
	v_mov_b32_e32 v34, v35
	v_mov_b32_e32 v39, v35
	v_mov_b32_e32 v40, v35
	v_mov_b32_e32 v41, v35
	v_mov_b32_e32 v42, v35
	v_mov_b32_e32 v43, v35
	v_mov_b32_e32 v44, v35
	v_mov_b32_e32 v45, v35
	v_mov_b32_e32 v46, v35
	v_mov_b32_e32 v47, v35
	v_mov_b32_e32 v48, v35
	v_mov_b32_e32 v49, v35
	v_mov_b32_e32 v50, v35
	v_mov_b32_e32 v51, v35
	v_mov_b32_e32 v52, v35
	v_mov_b32_e32 v53, v35
	v_mov_b32_e32 v54, v35
	v_mov_b32_e32 v55, v35
	v_mov_b32_e32 v56, v35
	v_mov_b32_e32 v57, v35
	v_mov_b32_e32 v58, v35
	v_mov_b32_e32 v59, v35
	v_mov_b32_e32 v60, v35
	v_mov_b32_e32 v61, v35
	v_mov_b32_e32 v62, v35
	v_mov_b32_e32 v63, v35
	v_mov_b32_e32 v64, v35
	v_mov_b32_e32 v65, v35
	v_readlane_b32 s13, v253, 15
	v_readlane_b32 s14, v253, 16
	v_readlane_b32 s15, v253, 17
	v_readlane_b32 s16, v253, 18
	v_readlane_b32 s17, v253, 19
	v_readlane_b32 s18, v253, 20
	v_readlane_b32 s19, v253, 21
	v_readlane_b32 s22, v253, 24
	v_readlane_b32 s23, v253, 25
	ds_write2st64_b64 v228, v[4:5], v[6:7] offset0:64 offset1:72
	s_cbranch_scc1 .LBB0_1026
	s_ashr_i32 s1, s0, 31
	s_add_i32 s10, s0, 0xffffc000
	s_cmpk_lt_i32 s0, 0x4000
	s_cselect_b64 s[8:9], -1, 0
	s_and_b64 vcc, s[8:9], exec
	v_readlane_b32 s8, v253, 52
	v_readlane_b32 s9, v253, 53
	s_cselect_b32 s12, s9, s5
	s_cselect_b32 s13, s8, s4
	s_cselect_b32 s9, s1, 0
	s_cselect_b32 s8, s0, s10
	s_lshl_b64 s[10:11], s[8:9], 12
	s_add_u32 s10, s13, s10
	s_addc_u32 s11, s12, s11
	v_lshlrev_b32_e32 v14, 4, v1
	global_load_dwordx4 v[2:5], v14, s[10:11] nt
	global_load_dwordx4 v[6:9], v14, s[10:11] offset:1024 nt
	global_load_dwordx4 v[10:13], v14, s[10:11] offset:2048 nt
	s_nop 0
	global_load_dwordx4 v[14:17], v14, s[10:11] offset:3072 nt
	s_waitcnt vmcnt(3)
	v_cvt_f32_f16_e32 v36, v3
	v_cvt_f32_f16_e32 v34, v2
	v_cvt_f32_f16_sdwa v37, v3 dst_sel:DWORD dst_unused:UNUSED_PAD src0_sel:WORD_1
	v_cvt_f32_f16_sdwa v35, v2 dst_sel:DWORD dst_unused:UNUSED_PAD src0_sel:WORD_1
	v_cvt_f32_f16_e32 v40, v5
	v_cvt_f32_f16_e32 v38, v4
	v_cvt_f32_f16_sdwa v41, v5 dst_sel:DWORD dst_unused:UNUSED_PAD src0_sel:WORD_1
	v_cvt_f32_f16_sdwa v39, v4 dst_sel:DWORD dst_unused:UNUSED_PAD src0_sel:WORD_1
	s_waitcnt vmcnt(2)
	v_cvt_f32_f16_e32 v44, v7
	v_cvt_f32_f16_e32 v42, v6
	v_cvt_f32_f16_sdwa v45, v7 dst_sel:DWORD dst_unused:UNUSED_PAD src0_sel:WORD_1
	v_cvt_f32_f16_sdwa v43, v6 dst_sel:DWORD dst_unused:UNUSED_PAD src0_sel:WORD_1
	v_cvt_f32_f16_e32 v48, v9
	v_cvt_f32_f16_e32 v46, v8
	v_cvt_f32_f16_sdwa v49, v9 dst_sel:DWORD dst_unused:UNUSED_PAD src0_sel:WORD_1
	v_cvt_f32_f16_sdwa v47, v8 dst_sel:DWORD dst_unused:UNUSED_PAD src0_sel:WORD_1
	s_waitcnt vmcnt(1)
	v_cvt_f32_f16_e32 v52, v11
	v_cvt_f32_f16_e32 v50, v10
	v_cvt_f32_f16_sdwa v53, v11 dst_sel:DWORD dst_unused:UNUSED_PAD src0_sel:WORD_1
	v_cvt_f32_f16_sdwa v51, v10 dst_sel:DWORD dst_unused:UNUSED_PAD src0_sel:WORD_1
	v_cvt_f32_f16_e32 v56, v13
	v_cvt_f32_f16_e32 v54, v12
	v_cvt_f32_f16_sdwa v57, v13 dst_sel:DWORD dst_unused:UNUSED_PAD src0_sel:WORD_1
	v_cvt_f32_f16_sdwa v55, v12 dst_sel:DWORD dst_unused:UNUSED_PAD src0_sel:WORD_1
	s_waitcnt vmcnt(0)
	v_cvt_f32_f16_e32 v60, v15
	v_cvt_f32_f16_e32 v58, v14
	v_cvt_f32_f16_sdwa v61, v15 dst_sel:DWORD dst_unused:UNUSED_PAD src0_sel:WORD_1
	v_cvt_f32_f16_sdwa v59, v14 dst_sel:DWORD dst_unused:UNUSED_PAD src0_sel:WORD_1
	v_cvt_f32_f16_e32 v64, v17
	v_cvt_f32_f16_e32 v62, v16
	v_cvt_f32_f16_sdwa v65, v17 dst_sel:DWORD dst_unused:UNUSED_PAD src0_sel:WORD_1
	v_cvt_f32_f16_sdwa v63, v16 dst_sel:DWORD dst_unused:UNUSED_PAD src0_sel:WORD_1
	s_cbranch_vccnz .LBB0_1026
	s_lshl_b64 s[8:9], s[8:9], 11
	s_lshl_b64 s[8:9], s[8:9], 2
	v_readlane_b32 s1, v253, 54
	s_add_u32 s8, s1, s8
	v_readlane_b32 s1, v253, 56
	v_lshlrev_b32_e32 v2, 3, v1
	s_addc_u32 s9, s1, s9
	v_lshlrev_b32_e32 v102, 2, v2
	s_add_u32 s10, s8, 0x1000000
	s_addc_u32 s11, s9, 0
	v_or_b32_e32 v110, 0x800, v102
	v_or_b32_e32 v126, 0x1800, v102
	global_load_dwordx4 v[2:5], v102, s[8:9] offset:16 nt
	global_load_dwordx4 v[6:9], v102, s[8:9] nt
	global_load_dwordx4 v[10:13], v102, s[8:9] offset:2064 nt
	global_load_dwordx4 v[14:17], v102, s[8:9] offset:2048 nt
	global_load_dwordx4 v[18:21], v102, s[10:11] offset:16 nt
	global_load_dwordx4 v[22:25], v102, s[10:11] nt
	v_or_b32_e32 v118, 0x1000, v102
	global_load_dwordx4 v[26:29], v110, s[10:11] offset:16 nt
	global_load_dwordx4 v[30:33], v110, s[10:11] nt
	global_load_dwordx4 v[66:69], v118, s[8:9] offset:16 nt
	global_load_dwordx4 v[70:73], v118, s[8:9] nt
	global_load_dwordx4 v[74:77], v118, s[10:11] offset:16 nt
	global_load_dwordx4 v[78:81], v118, s[10:11] nt
	global_load_dwordx4 v[82:85], v126, s[8:9] offset:16 nt
	global_load_dwordx4 v[86:89], v126, s[8:9] nt
	global_load_dwordx4 v[90:93], v126, s[10:11] nt
	global_load_dwordx4 v[94:97], v126, s[10:11] offset:16 nt
	s_add_u32 s8, s8, 0x2000000
	s_addc_u32 s9, s9, 0
	global_load_dwordx4 v[98:101], v102, s[8:9] nt
	s_nop 0
	global_load_dwordx4 v[102:105], v102, s[8:9] offset:16 nt
	s_nop 0
	global_load_dwordx4 v[106:109], v110, s[8:9] nt
	s_nop 0
	global_load_dwordx4 v[110:113], v110, s[8:9] offset:16 nt
	s_nop 0
	global_load_dwordx4 v[114:117], v118, s[8:9] nt
	s_nop 0
	global_load_dwordx4 v[118:121], v118, s[8:9] offset:16 nt
	s_nop 0
	global_load_dwordx4 v[122:125], v126, s[8:9] nt
	s_nop 0
	global_load_dwordx4 v[126:129], v126, s[8:9] offset:16 nt
	s_waitcnt vmcnt(17)
	v_pk_add_f32 v[12:13], v[12:13], v[28:29]
	v_pk_add_f32 v[4:5], v[4:5], v[20:21]
	v_pk_add_f32 v[8:9], v[8:9], v[24:25]
	v_pk_add_f32 v[6:7], v[6:7], v[22:23]
	v_pk_add_f32 v[2:3], v[2:3], v[18:19]
	s_waitcnt vmcnt(16)
	v_pk_add_f32 v[16:17], v[16:17], v[32:33]
	v_pk_add_f32 v[14:15], v[14:15], v[30:31]
	v_pk_add_f32 v[10:11], v[10:11], v[26:27]
	s_waitcnt vmcnt(12)
	v_pk_add_f32 v[18:19], v[72:73], v[80:81]
	v_pk_add_f32 v[20:21], v[70:71], v[78:79]
	v_pk_add_f32 v[22:23], v[68:69], v[76:77]
	v_pk_add_f32 v[24:25], v[66:67], v[74:75]
	s_waitcnt vmcnt(9)
	v_pk_add_f32 v[26:27], v[88:89], v[92:93]
	v_pk_add_f32 v[28:29], v[86:87], v[90:91]
	s_waitcnt vmcnt(8)
	v_pk_add_f32 v[30:31], v[84:85], v[96:97]
	v_pk_add_f32 v[32:33], v[82:83], v[94:95]
	s_waitcnt vmcnt(7)
	v_pk_add_f32 v[8:9], v[8:9], v[100:101]
	v_pk_add_f32 v[6:7], v[6:7], v[98:99]
	s_waitcnt vmcnt(6)
	v_pk_add_f32 v[4:5], v[4:5], v[104:105]
	v_pk_add_f32 v[2:3], v[2:3], v[102:103]
	s_waitcnt vmcnt(5)
	v_pk_add_f32 v[16:17], v[16:17], v[108:109]
	v_pk_add_f32 v[14:15], v[14:15], v[106:107]
	s_waitcnt vmcnt(4)
	v_pk_add_f32 v[12:13], v[12:13], v[112:113]
	v_pk_add_f32 v[10:11], v[10:11], v[110:111]
	s_waitcnt vmcnt(3)
	v_pk_add_f32 v[18:19], v[18:19], v[116:117]
	v_pk_add_f32 v[20:21], v[20:21], v[114:115]
	s_waitcnt vmcnt(2)
	v_pk_add_f32 v[22:23], v[22:23], v[120:121]
	v_pk_add_f32 v[24:25], v[24:25], v[118:119]
	s_waitcnt vmcnt(1)
	v_pk_add_f32 v[26:27], v[26:27], v[124:125]
	v_pk_add_f32 v[28:29], v[28:29], v[122:123]
	s_waitcnt vmcnt(0)
	v_pk_add_f32 v[30:31], v[30:31], v[128:129]
	v_pk_add_f32 v[32:33], v[32:33], v[126:127]
	v_pk_add_f32 v[36:37], v[8:9], v[36:37]
	v_pk_add_f32 v[34:35], v[6:7], v[34:35]
	v_pk_add_f32 v[40:41], v[4:5], v[40:41]
	v_pk_add_f32 v[38:39], v[2:3], v[38:39]
	v_pk_add_f32 v[44:45], v[16:17], v[44:45]
	v_pk_add_f32 v[42:43], v[14:15], v[42:43]
	v_pk_add_f32 v[48:49], v[12:13], v[48:49]
	v_pk_add_f32 v[46:47], v[10:11], v[46:47]
	v_pk_add_f32 v[52:53], v[18:19], v[52:53]
	v_pk_add_f32 v[50:51], v[20:21], v[50:51]
	v_pk_add_f32 v[56:57], v[22:23], v[56:57]
	v_pk_add_f32 v[54:55], v[24:25], v[54:55]
	v_pk_add_f32 v[60:61], v[26:27], v[60:61]
	v_pk_add_f32 v[58:59], v[28:29], v[58:59]
	v_pk_add_f32 v[64:65], v[30:31], v[64:65]
	v_pk_add_f32 v[62:63], v[32:33], v[62:63]

; #define LAS __attribute__((address_space(3)))
; __device__ __forceinline__ u32x2 f32x4_to_h4(f32x4 v) { return __builtin_bit_cast(u32x2, __builtin_convertvector(v, f16x4)); }
; template <bool COMBINE, bool SRC_F32>
; __device__ __forceinline__ void norm_phase(LAS unsigned char* lds, const void* src_lat, const void* src_ctx, _Float16* xw_ctx, const float* part, int nrows, const float* g, const float* modl, int shift_idx, int scale_idx, bf16* HN, int tid, int lane, int wave) {
;     ...
;         const f32x4 gg = *(const f32x4*)(g + 4 * tid);
;         f32x4 s1[9], s0[9];
; #pragma unroll
;         for (int r = 0; r < 9; ++r) { s1[r] = *(const f32x4*)(modl + (size_t)r * DMODW + scale_idx * D + 4 * tid); s0[r] = *(const f32x4*)(modl + (size_t)r * DMODW + shift_idx * D + 4 * tid); }
; #pragma unroll
;         for (int r = 0; r < 9; ++r) { *(LAS u32x2*)(Gs + r * D + 4 * tid) = f32x4_to_h4(gg * (1.0f + s1[r])); *(LAS u32x2*)(Ss + r * D + 4 * tid) = f32x4_to_h4(s0[r]); }
.LBB0_1371:
	v_readfirstlane_b32 s76, v0
	s_lshr_b32 s96, s76, 6
	s_add_u32 s6, s88, 0x18400000
	s_addc_u32 s7, s89, 0
	s_cmp_lt_i32 s90, 12
	s_cselect_b64 s[2:3], -1, 0
	s_and_b64 s[0:1], s[2:3], s[0:1]
	s_andn2_b64 vcc, exec, s[0:1]
	s_cbranch_vccnz .LBB0_1384
	v_readlane_b32 s8, v253, 10
	s_waitcnt vmcnt(0)
	v_lshlrev_b32_e32 v34, 4, v0
	v_mov_b32_e32 v35, 0
	v_readlane_b32 s20, v253, 22
	v_readlane_b32 s21, v253, 23
	v_lshl_add_u64 v[76:77], s[88:89], 0, v[34:35]
	s_lshl_b32 s0, s86, 3
	v_lshl_add_u64 v[2:3], s[20:21], 0, v[34:35]
	v_add_co_u32_e32 v2, vcc, 0x6000, v2
	s_add_i32 s0, s96, s0
	s_nop 0
	v_addc_co_u32_e32 v3, vcc, 0, v3, vcc
	v_add_co_u32_e32 v6, vcc, 0x1a4000, v76
	global_load_dwordx4 v[2:5], v[2:3], off
	s_nop 0
	v_addc_co_u32_e32 v7, vcc, 0, v77, vcc
	v_add_co_u32_e32 v10, vcc, 0x1a2000, v76
	v_add_u32_e32 v34, 0x9000, v228
	s_nop 0
	v_addc_co_u32_e32 v11, vcc, 0, v77, vcc
	v_add_co_u32_e32 v14, vcc, 0x1b6000, v76
	global_load_dwordx4 v[6:9], v[6:7], off
	s_nop 0
	global_load_dwordx4 v[10:13], v[10:11], off
	v_addc_co_u32_e32 v15, vcc, 0, v77, vcc
	v_add_co_u32_e32 v18, vcc, 0x1b4000, v76
	s_cmpk_lt_i32 s0, 0x4800
	s_nop 0
	v_addc_co_u32_e32 v19, vcc, 0, v77, vcc
	v_add_co_u32_e32 v22, vcc, 0x1c8000, v76
	global_load_dwordx4 v[14:17], v[14:15], off
	s_nop 0
	global_load_dwordx4 v[18:21], v[18:19], off
	v_addc_co_u32_e32 v23, vcc, 0, v77, vcc
	v_add_co_u32_e32 v26, vcc, 0x1c6000, v76
	s_cselect_b64 s[4:5], -1, 0
	s_nop 0
	v_addc_co_u32_e32 v27, vcc, 0, v77, vcc
	v_add_co_u32_e32 v30, vcc, 0x1da000, v76
	global_load_dwordx4 v[22:25], v[22:23], off
	s_nop 0
	global_load_dwordx4 v[26:29], v[26:27], off
	v_addc_co_u32_e32 v31, vcc, 0, v77, vcc
	v_add_co_u32_e32 v36, vcc, 0x1d8000, v76
	s_cmpk_gt_i32 s0, 0x47ff
	s_nop 0
	v_addc_co_u32_e32 v37, vcc, 0, v77, vcc
	v_add_co_u32_e32 v40, vcc, 0x1ec000, v76
	global_load_dwordx4 v[30:33], v[30:31], off
	s_nop 0
	global_load_dwordx4 v[36:39], v[36:37], off
	v_addc_co_u32_e32 v41, vcc, 0, v77, vcc
	v_add_co_u32_e32 v44, vcc, 0x1ea000, v76
	v_readlane_b32 s9, v253, 11
	s_nop 0
	v_addc_co_u32_e32 v45, vcc, 0, v77, vcc
	v_add_co_u32_e32 v48, vcc, 0x1fe000, v76
	global_load_dwordx4 v[40:43], v[40:41], off
	s_nop 0
	global_load_dwordx4 v[44:47], v[44:45], off
	v_addc_co_u32_e32 v49, vcc, 0, v77, vcc
	v_add_co_u32_e32 v52, vcc, 0x1fc000, v76
	v_readlane_b32 s10, v253, 12
	s_nop 0
	v_addc_co_u32_e32 v53, vcc, 0, v77, vcc
	v_add_co_u32_e32 v56, vcc, 0x210000, v76
	global_load_dwordx4 v[48:51], v[48:49], off
	s_nop 0
	global_load_dwordx4 v[52:55], v[52:53], off
	v_addc_co_u32_e32 v57, vcc, 0, v77, vcc
	v_add_co_u32_e32 v60, vcc, 0x20e000, v76
	v_readlane_b32 s11, v253, 13
	s_nop 0
	v_addc_co_u32_e32 v61, vcc, 0, v77, vcc
	v_add_co_u32_e32 v64, vcc, 0x222000, v76
	global_load_dwordx4 v[56:59], v[56:57], off
	s_nop 0
	global_load_dwordx4 v[60:63], v[60:61], off
	v_addc_co_u32_e32 v65, vcc, 0, v77, vcc
	v_add_co_u32_e32 v68, vcc, 0x220000, v76
	global_load_dwordx4 v[64:67], v[64:65], off
	s_nop 0
	v_addc_co_u32_e32 v69, vcc, 0, v77, vcc
	v_add_co_u32_e32 v72, vcc, 0x234000, v76
	global_load_dwordx4 v[68:71], v[68:69], off
	s_nop 0
	v_addc_co_u32_e32 v73, vcc, 0, v77, vcc
	global_load_dwordx4 v[72:75], v[72:73], off
	v_add_co_u32_e32 v76, vcc, 0x232000, v76
	v_readlane_b32 s12, v253, 14
	s_nop 0
	v_addc_co_u32_e32 v77, vcc, 0, v77, vcc
	global_load_dwordx4 v[76:79], v[76:77], off
	s_waitcnt vmcnt(17)
	v_pk_add_f32 v[8:9], v[8:9], 1.0 op_sel_hi:[1,0]
	v_pk_add_f32 v[6:7], v[6:7], 1.0 op_sel_hi:[1,0]
	v_pk_mul_f32 v[8:9], v[4:5], v[8:9]
	v_pk_mul_f32 v[6:7], v[2:3], v[6:7]
	v_cvt_pk_f16_f32 v9, v8, v9
	v_cvt_pk_f16_f32 v8, v6, v7
	s_waitcnt vmcnt(16)
	v_cvt_pk_f16_f32 v7, v12, v13
	v_cvt_pk_f16_f32 v6, v10, v11
	v_readlane_b32 s13, v253, 15
	s_waitcnt vmcnt(15)
	v_pk_add_f32 v[10:11], v[16:17], 1.0 op_sel_hi:[1,0]
	v_pk_add_f32 v[12:13], v[14:15], 1.0 op_sel_hi:[1,0]
	v_pk_mul_f32 v[10:11], v[4:5], v[10:11]
	v_pk_mul_f32 v[12:13], v[2:3], v[12:13]
	v_cvt_pk_f16_f32 v11, v10, v11
	v_cvt_pk_f16_f32 v10, v12, v13
	ds_write2st64_b64 v228, v[8:9], v[10:11] offset1:8
	s_waitcnt vmcnt(14)
	v_cvt_pk_f16_f32 v9, v20, v21
	v_cvt_pk_f16_f32 v8, v18, v19
	v_readlane_b32 s14, v253, 16
	s_waitcnt vmcnt(13)
	v_pk_add_f32 v[10:11], v[24:25], 1.0 op_sel_hi:[1,0]
	v_pk_add_f32 v[12:13], v[22:23], 1.0 op_sel_hi:[1,0]
	v_pk_mul_f32 v[10:11], v[4:5], v[10:11]
	v_pk_mul_f32 v[12:13], v[2:3], v[12:13]
	v_cvt_pk_f16_f32 v11, v10, v11
	v_cvt_pk_f16_f32 v10, v12, v13
	s_waitcnt vmcnt(12)
	v_cvt_pk_f16_f32 v13, v28, v29
	v_cvt_pk_f16_f32 v12, v26, v27
	ds_write2st64_b64 v228, v[8:9], v[12:13] offset0:80 offset1:88
	v_readlane_b32 s15, v253, 17
	s_waitcnt vmcnt(11)
	v_pk_add_f32 v[8:9], v[32:33], 1.0 op_sel_hi:[1,0]
	v_pk_add_f32 v[12:13], v[30:31], 1.0 op_sel_hi:[1,0]
	v_pk_mul_f32 v[8:9], v[4:5], v[8:9]
	v_pk_mul_f32 v[12:13], v[2:3], v[12:13]
	v_cvt_pk_f16_f32 v9, v8, v9
	v_cvt_pk_f16_f32 v8, v12, v13
	ds_write2st64_b64 v228, v[10:11], v[8:9] offset0:16 offset1:24
	s_waitcnt vmcnt(10)
	v_cvt_pk_f16_f32 v9, v38, v39
	v_cvt_pk_f16_f32 v8, v36, v37
	v_mov_b32_e32 v36, v35
	s_waitcnt vmcnt(9)
	v_pk_add_f32 v[10:11], v[42:43], 1.0 op_sel_hi:[1,0]
	v_pk_add_f32 v[12:13], v[40:41], 1.0 op_sel_hi:[1,0]
	v_pk_mul_f32 v[10:11], v[4:5], v[10:11]
	v_pk_mul_f32 v[12:13], v[2:3], v[12:13]
	v_cvt_pk_f16_f32 v11, v10, v11
	v_cvt_pk_f16_f32 v10, v12, v13
	s_waitcnt vmcnt(8)
	v_cvt_pk_f16_f32 v13, v46, v47
	v_cvt_pk_f16_f32 v12, v44, v45
	ds_write2st64_b64 v228, v[8:9], v[12:13] offset0:96 offset1:104
	v_mov_b32_e32 v37, v35
	s_waitcnt vmcnt(7)
; #define LAS __attribute__((address_space(3)))
; __device__ __forceinline__ u32x2 f32x4_to_h4(f32x4 v) { return __builtin_bit_cast(u32x2, __builtin_convertvector(v, f16x4)); }
; template <bool COMBINE, bool SRC_F32>
; __device__ __forceinline__ void norm_phase(LAS unsigned char* lds, const void* src_lat, const void* src_ctx, _Float16* xw_ctx, const float* part, int nrows, const float* g, const float* modl, int shift_idx, int scale_idx, bf16* HN, int tid, int lane, int wave) {
;     ...
;         for (int r = 0; r < 9; ++r) { *(LAS u32x2*)(Gs + r * D + 4 * tid) = f32x4_to_h4(gg * (1.0f + s1[r])); *(LAS u32x2*)(Ss + r * D + 4 * tid) = f32x4_to_h4(s0[r]); }
;     ...
;     if (gw < nrows) NORM_LOAD(v, gw);
	v_pk_add_f32 v[8:9], v[50:51], 1.0 op_sel_hi:[1,0]
	v_pk_add_f32 v[12:13], v[48:49], 1.0 op_sel_hi:[1,0]
	v_pk_mul_f32 v[8:9], v[4:5], v[8:9]
	v_pk_mul_f32 v[12:13], v[2:3], v[12:13]
	v_cvt_pk_f16_f32 v9, v8, v9
	v_cvt_pk_f16_f32 v8, v12, v13
	ds_write2st64_b64 v228, v[10:11], v[8:9] offset0:32 offset1:40
	s_waitcnt vmcnt(6)
	v_cvt_pk_f16_f32 v9, v54, v55
	v_cvt_pk_f16_f32 v8, v52, v53
	v_mov_b32_e32 v38, v35
	s_waitcnt vmcnt(5)
	v_pk_add_f32 v[10:11], v[58:59], 1.0 op_sel_hi:[1,0]
	v_pk_add_f32 v[12:13], v[56:57], 1.0 op_sel_hi:[1,0]
	v_pk_mul_f32 v[10:11], v[4:5], v[10:11]
	v_pk_mul_f32 v[12:13], v[2:3], v[12:13]
	v_cvt_pk_f16_f32 v11, v10, v11
	v_cvt_pk_f16_f32 v10, v12, v13
	s_waitcnt vmcnt(4)
	v_cvt_pk_f16_f32 v13, v62, v63
	v_cvt_pk_f16_f32 v12, v60, v61
	ds_write2st64_b64 v228, v[8:9], v[12:13] offset0:112 offset1:120
	s_waitcnt vmcnt(3)
	v_pk_add_f32 v[8:9], v[66:67], 1.0 op_sel_hi:[1,0]
	v_pk_add_f32 v[12:13], v[64:65], 1.0 op_sel_hi:[1,0]
	v_pk_mul_f32 v[8:9], v[4:5], v[8:9]
	v_pk_mul_f32 v[12:13], v[2:3], v[12:13]
	v_cvt_pk_f16_f32 v9, v8, v9
	v_cvt_pk_f16_f32 v8, v12, v13
	ds_write2st64_b64 v228, v[10:11], v[8:9] offset0:48 offset1:56
	s_waitcnt vmcnt(1)
	v_pk_add_f32 v[10:11], v[74:75], 1.0 op_sel_hi:[1,0]
	v_pk_add_f32 v[12:13], v[72:73], 1.0 op_sel_hi:[1,0]
	v_pk_mul_f32 v[4:5], v[4:5], v[10:11]
	v_pk_mul_f32 v[2:3], v[2:3], v[12:13]
	v_cvt_pk_f16_f32 v9, v70, v71
	v_cvt_pk_f16_f32 v8, v68, v69
	v_cvt_pk_f16_f32 v5, v4, v5
	v_cvt_pk_f16_f32 v4, v2, v3
	s_waitcnt vmcnt(0)
	v_cvt_pk_f16_f32 v3, v78, v79
	v_cvt_pk_f16_f32 v2, v76, v77
	ds_write2st64_b64 v34, v[8:9], v[2:3] offset0:56 offset1:64
	v_mov_b32_e32 v34, v35
	v_mov_b32_e32 v39, v35
	v_mov_b32_e32 v40, v35
	v_mov_b32_e32 v41, v35
	v_mov_b32_e32 v42, v35
	v_mov_b32_e32 v43, v35
	v_mov_b32_e32 v44, v35
	v_mov_b32_e32 v45, v35
	v_mov_b32_e32 v46, v35
	v_mov_b32_e32 v47, v35
	v_mov_b32_e32 v48, v35
	v_mov_b32_e32 v49, v35
	v_mov_b32_e32 v50, v35
	v_mov_b32_e32 v51, v35
	v_mov_b32_e32 v52, v35
	v_mov_b32_e32 v53, v35
	v_mov_b32_e32 v54, v35
	v_mov_b32_e32 v55, v35
	v_mov_b32_e32 v56, v35
	v_mov_b32_e32 v57, v35
	v_mov_b32_e32 v58, v35
	v_mov_b32_e32 v59, v35
	v_mov_b32_e32 v60, v35
	v_mov_b32_e32 v61, v35
	v_mov_b32_e32 v62, v35
	v_mov_b32_e32 v63, v35
	v_mov_b32_e32 v64, v35
	v_mov_b32_e32 v65, v35
	v_readlane_b32 s16, v253, 18
	v_readlane_b32 s17, v253, 19
	v_readlane_b32 s18, v253, 20
	v_readlane_b32 s19, v253, 21
	v_readlane_b32 s22, v253, 24
	v_readlane_b32 s23, v253, 25
	ds_write2st64_b64 v228, v[4:5], v[6:7] offset0:64 offset1:72
	s_cbranch_scc1 .LBB0_1375
	s_ashr_i32 s1, s0, 31
	s_add_i32 s10, s0, 0xffffc000
	s_cmpk_lt_i32 s0, 0x4000
	s_cselect_b64 s[8:9], -1, 0
	s_and_b64 vcc, s[8:9], exec
	v_readlane_b32 s8, v253, 52
	v_readlane_b32 s9, v253, 53
	s_cselect_b32 s12, s9, s7
	s_cselect_b32 s13, s8, s6
	s_cselect_b32 s9, s1, 0
	s_cselect_b32 s8, s0, s10
	s_lshl_b64 s[10:11], s[8:9], 12
	s_add_u32 s10, s13, s10
	s_addc_u32 s11, s12, s11
	v_lshlrev_b32_e32 v14, 4, v1
	global_load_dwordx4 v[2:5], v14, s[10:11] nt
	global_load_dwordx4 v[6:9], v14, s[10:11] offset:1024 nt
	global_load_dwordx4 v[10:13], v14, s[10:11] offset:2048 nt
	s_nop 0
	global_load_dwordx4 v[14:17], v14, s[10:11] offset:3072 nt
	s_waitcnt vmcnt(3)
	v_cvt_f32_f16_e32 v36, v3
	v_cvt_f32_f16_e32 v34, v2
	v_cvt_f32_f16_sdwa v37, v3 dst_sel:DWORD dst_unused:UNUSED_PAD src0_sel:WORD_1
	v_cvt_f32_f16_sdwa v35, v2 dst_sel:DWORD dst_unused:UNUSED_PAD src0_sel:WORD_1
	v_cvt_f32_f16_e32 v40, v5
	v_cvt_f32_f16_e32 v38, v4
	v_cvt_f32_f16_sdwa v41, v5 dst_sel:DWORD dst_unused:UNUSED_PAD src0_sel:WORD_1
	v_cvt_f32_f16_sdwa v39, v4 dst_sel:DWORD dst_unused:UNUSED_PAD src0_sel:WORD_1
	s_waitcnt vmcnt(2)
	v_cvt_f32_f16_e32 v44, v7
	v_cvt_f32_f16_e32 v42, v6
	v_cvt_f32_f16_sdwa v45, v7 dst_sel:DWORD dst_unused:UNUSED_PAD src0_sel:WORD_1
	v_cvt_f32_f16_sdwa v43, v6 dst_sel:DWORD dst_unused:UNUSED_PAD src0_sel:WORD_1
	v_cvt_f32_f16_e32 v48, v9
	v_cvt_f32_f16_e32 v46, v8
	v_cvt_f32_f16_sdwa v49, v9 dst_sel:DWORD dst_unused:UNUSED_PAD src0_sel:WORD_1
	v_cvt_f32_f16_sdwa v47, v8 dst_sel:DWORD dst_unused:UNUSED_PAD src0_sel:WORD_1
	s_waitcnt vmcnt(1)
	v_cvt_f32_f16_e32 v52, v11
	v_cvt_f32_f16_e32 v50, v10
	v_cvt_f32_f16_sdwa v53, v11 dst_sel:DWORD dst_unused:UNUSED_PAD src0_sel:WORD_1
	v_cvt_f32_f16_sdwa v51, v10 dst_sel:DWORD dst_unused:UNUSED_PAD src0_sel:WORD_1
	v_cvt_f32_f16_e32 v56, v13
	v_cvt_f32_f16_e32 v54, v12
	v_cvt_f32_f16_sdwa v57, v13 dst_sel:DWORD dst_unused:UNUSED_PAD src0_sel:WORD_1
	v_cvt_f32_f16_sdwa v55, v12 dst_sel:DWORD dst_unused:UNUSED_PAD src0_sel:WORD_1
	s_waitcnt vmcnt(0)
	v_cvt_f32_f16_e32 v60, v15
	v_cvt_f32_f16_e32 v58, v14
	v_cvt_f32_f16_sdwa v61, v15 dst_sel:DWORD dst_unused:UNUSED_PAD src0_sel:WORD_1
	v_cvt_f32_f16_sdwa v59, v14 dst_sel:DWORD dst_unused:UNUSED_PAD src0_sel:WORD_1
	v_cvt_f32_f16_e32 v64, v17
	v_cvt_f32_f16_e32 v62, v16
	v_cvt_f32_f16_sdwa v65, v17 dst_sel:DWORD dst_unused:UNUSED_PAD src0_sel:WORD_1
	v_cvt_f32_f16_sdwa v63, v16 dst_sel:DWORD dst_unused:UNUSED_PAD src0_sel:WORD_1
	s_cbranch_vccnz .LBB0_1375
	s_lshl_b64 s[8:9], s[8:9], 11
	s_lshl_b64 s[8:9], s[8:9], 2
	v_readlane_b32 s1, v253, 54
	s_add_u32 s8, s1, s8
	v_readlane_b32 s1, v253, 56
	v_lshlrev_b32_e32 v2, 3, v1
	s_addc_u32 s9, s1, s9
	v_lshlrev_b32_e32 v102, 2, v2
	s_add_u32 s10, s8, 0x1000000
	s_addc_u32 s11, s9, 0
	v_or_b32_e32 v110, 0x800, v102
	v_or_b32_e32 v126, 0x1800, v102
	global_load_dwordx4 v[2:5], v102, s[8:9] offset:16 nt
	global_load_dwordx4 v[6:9], v102, s[8:9] nt
	global_load_dwordx4 v[10:13], v102, s[8:9] offset:2064 nt
	global_load_dwordx4 v[14:17], v102, s[8:9] offset:2048 nt
	global_load_dwordx4 v[18:21], v102, s[10:11] offset:16 nt
	global_load_dwordx4 v[22:25], v102, s[10:11] nt
	v_or_b32_e32 v118, 0x1000, v102
	global_load_dwordx4 v[26:29], v110, s[10:11] offset:16 nt
	global_load_dwordx4 v[30:33], v110, s[10:11] nt
	global_load_dwordx4 v[66:69], v118, s[8:9] offset:16 nt
	global_load_dwordx4 v[70:73], v118, s[8:9] nt
	global_load_dwordx4 v[74:77], v118, s[10:11] offset:16 nt
	global_load_dwordx4 v[78:81], v118, s[10:11] nt
	global_load_dwordx4 v[82:85], v126, s[8:9] offset:16 nt
	global_load_dwordx4 v[86:89], v126, s[8:9] nt
	global_load_dwordx4 v[90:93], v126, s[10:11] nt
	global_load_dwordx4 v[94:97], v126, s[10:11] offset:16 nt
	s_add_u32 s8, s8, 0x2000000
	s_addc_u32 s9, s9, 0
	global_load_dwordx4 v[98:101], v102, s[8:9] nt
	s_nop 0
	global_load_dwordx4 v[102:105], v102, s[8:9] offset:16 nt
	s_nop 0
	global_load_dwordx4 v[106:109], v110, s[8:9] nt
	s_nop 0
	global_load_dwordx4 v[110:113], v110, s[8:9] offset:16 nt
	s_nop 0
	global_load_dwordx4 v[114:117], v118, s[8:9] nt
	s_nop 0
	global_load_dwordx4 v[118:121], v118, s[8:9] offset:16 nt
	s_nop 0
	global_load_dwordx4 v[122:125], v126, s[8:9] nt
	s_nop 0
	global_load_dwordx4 v[126:129], v126, s[8:9] offset:16 nt
	s_waitcnt vmcnt(17)
	v_pk_add_f32 v[12:13], v[12:13], v[28:29]
	v_pk_add_f32 v[4:5], v[4:5], v[20:21]
	v_pk_add_f32 v[8:9], v[8:9], v[24:25]
	v_pk_add_f32 v[6:7], v[6:7], v[22:23]
	v_pk_add_f32 v[2:3], v[2:3], v[18:19]
	s_waitcnt vmcnt(16)
	v_pk_add_f32 v[16:17], v[16:17], v[32:33]
	v_pk_add_f32 v[14:15], v[14:15], v[30:31]
	v_pk_add_f32 v[10:11], v[10:11], v[26:27]
	s_waitcnt vmcnt(12)
	v_pk_add_f32 v[18:19], v[72:73], v[80:81]
	v_pk_add_f32 v[20:21], v[70:71], v[78:79]
	v_pk_add_f32 v[22:23], v[68:69], v[76:77]
	v_pk_add_f32 v[24:25], v[66:67], v[74:75]
	s_waitcnt vmcnt(9)
	v_pk_add_f32 v[26:27], v[88:89], v[92:93]
	v_pk_add_f32 v[28:29], v[86:87], v[90:91]
	s_waitcnt vmcnt(8)
	v_pk_add_f32 v[30:31], v[84:85], v[96:97]
	v_pk_add_f32 v[32:33], v[82:83], v[94:95]
	s_waitcnt vmcnt(7)
	v_pk_add_f32 v[8:9], v[8:9], v[100:101]
	v_pk_add_f32 v[6:7], v[6:7], v[98:99]
	s_waitcnt vmcnt(6)
	v_pk_add_f32 v[4:5], v[4:5], v[104:105]
	v_pk_add_f32 v[2:3], v[2:3], v[102:103]
	s_waitcnt vmcnt(5)
	v_pk_add_f32 v[16:17], v[16:17], v[108:109]
	v_pk_add_f32 v[14:15], v[14:15], v[106:107]
	s_waitcnt vmcnt(4)
	v_pk_add_f32 v[12:13], v[12:13], v[112:113]
	v_pk_add_f32 v[10:11], v[10:11], v[110:111]
	s_waitcnt vmcnt(3)
	v_pk_add_f32 v[18:19], v[18:19], v[116:117]
	v_pk_add_f32 v[20:21], v[20:21], v[114:115]
	s_waitcnt vmcnt(2)
	v_pk_add_f32 v[22:23], v[22:23], v[120:121]
	v_pk_add_f32 v[24:25], v[24:25], v[118:119]
	s_waitcnt vmcnt(1)
	v_pk_add_f32 v[26:27], v[26:27], v[124:125]
	v_pk_add_f32 v[28:29], v[28:29], v[122:123]
	s_waitcnt vmcnt(0)
	v_pk_add_f32 v[30:31], v[30:31], v[128:129]
	v_pk_add_f32 v[32:33], v[32:33], v[126:127]
	v_pk_add_f32 v[36:37], v[8:9], v[36:37]
	v_pk_add_f32 v[34:35], v[6:7], v[34:35]
	v_pk_add_f32 v[40:41], v[4:5], v[40:41]
	v_pk_add_f32 v[38:39], v[2:3], v[38:39]
	v_pk_add_f32 v[44:45], v[16:17], v[44:45]
	v_pk_add_f32 v[42:43], v[14:15], v[42:43]
	v_pk_add_f32 v[48:49], v[12:13], v[48:49]
	v_pk_add_f32 v[46:47], v[10:11], v[46:47]
	v_pk_add_f32 v[52:53], v[18:19], v[52:53]
	v_pk_add_f32 v[50:51], v[20:21], v[50:51]
	v_pk_add_f32 v[56:57], v[22:23], v[56:57]
	v_pk_add_f32 v[54:55], v[24:25], v[54:55]
	v_pk_add_f32 v[60:61], v[26:27], v[60:61]
	v_pk_add_f32 v[58:59], v[28:29], v[58:59]
	v_pk_add_f32 v[64:65], v[30:31], v[64:65]
	v_pk_add_f32 v[62:63], v[32:33], v[62:63]

; template <bool COMBINE, bool SRC_F32>
; __device__ __forceinline__ void norm_phase(LAS unsigned char* lds, const void* src_lat, const void* src_ctx, _Float16* xw_ctx, const float* part, int nrows, const float* g, const float* modl, int shift_idx, int scale_idx, bf16* HN, int tid, int lane, int wave) {
;     ...
;     for (int row = gw; row < nrows; row += NGW) {
;         if (row + NGW < nrows) NORM_LOAD(nv, row + NGW);
.LBB0_1378:
	s_add_i32 s14, s4, s8
	s_add_i32 s0, s14, 0x4000
	s_cmpk_gt_i32 s0, 0x47ff
	s_cselect_b64 s[12:13], -1, 0
	s_and_b64 vcc, exec, s[12:13]
	s_cbranch_vccnz .LBB0_1381
	s_ashr_i32 s1, s0, 31
	s_cmpk_lt_i32 s0, 0x4000
	s_cselect_b64 s[16:17], -1, 0
	s_and_b64 vcc, s[16:17], exec
	v_readlane_b32 s16, v253, 52
	v_readlane_b32 s17, v253, 53
	s_cselect_b32 s1, s1, 0
	s_cselect_b32 s0, s0, s14
	s_cselect_b32 s15, s17, s7
	s_cselect_b32 s18, s16, s6
	s_lshl_b64 s[16:17], s[0:1], 12
	s_add_u32 s16, s18, s16
	s_addc_u32 s17, s15, s17
	v_lshlrev_b32_e32 v2, 1, v66
	global_load_dwordx4 v[8:11], v2, s[16:17] nt
	global_load_dwordx4 v[16:19], v2, s[16:17] offset:1024 nt
	global_load_dwordx4 v[24:27], v2, s[16:17] offset:2048 nt
	global_load_dwordx4 v[80:83], v2, s[16:17] offset:3072 nt
	s_waitcnt vmcnt(3)
	v_cvt_f32_f16_e32 v4, v9
	v_cvt_f32_f16_e32 v2, v8
	v_cvt_f32_f16_sdwa v5, v9 dst_sel:DWORD dst_unused:UNUSED_PAD src0_sel:WORD_1
	v_cvt_f32_f16_sdwa v3, v8 dst_sel:DWORD dst_unused:UNUSED_PAD src0_sel:WORD_1
	v_cvt_f32_f16_e32 v8, v11
	v_cvt_f32_f16_e32 v6, v10
	v_cvt_f32_f16_sdwa v9, v11 dst_sel:DWORD dst_unused:UNUSED_PAD src0_sel:WORD_1
	v_cvt_f32_f16_sdwa v7, v10 dst_sel:DWORD dst_unused:UNUSED_PAD src0_sel:WORD_1
	s_waitcnt vmcnt(2)
	v_cvt_f32_f16_e32 v12, v17
	v_cvt_f32_f16_e32 v10, v16
	v_cvt_f32_f16_sdwa v13, v17 dst_sel:DWORD dst_unused:UNUSED_PAD src0_sel:WORD_1
	v_cvt_f32_f16_sdwa v11, v16 dst_sel:DWORD dst_unused:UNUSED_PAD src0_sel:WORD_1
	v_cvt_f32_f16_e32 v16, v19
	v_cvt_f32_f16_e32 v14, v18
	v_cvt_f32_f16_sdwa v17, v19 dst_sel:DWORD dst_unused:UNUSED_PAD src0_sel:WORD_1
	v_cvt_f32_f16_sdwa v15, v18 dst_sel:DWORD dst_unused:UNUSED_PAD src0_sel:WORD_1
	s_waitcnt vmcnt(1)
	v_cvt_f32_f16_e32 v20, v25
	v_cvt_f32_f16_e32 v18, v24
	v_cvt_f32_f16_sdwa v21, v25 dst_sel:DWORD dst_unused:UNUSED_PAD src0_sel:WORD_1
	v_cvt_f32_f16_sdwa v19, v24 dst_sel:DWORD dst_unused:UNUSED_PAD src0_sel:WORD_1
	v_cvt_f32_f16_e32 v24, v27
	v_cvt_f32_f16_e32 v22, v26
	v_cvt_f32_f16_sdwa v25, v27 dst_sel:DWORD dst_unused:UNUSED_PAD src0_sel:WORD_1
	v_cvt_f32_f16_sdwa v23, v26 dst_sel:DWORD dst_unused:UNUSED_PAD src0_sel:WORD_1
	s_waitcnt vmcnt(0)
	v_cvt_f32_f16_e32 v28, v81
	v_cvt_f32_f16_e32 v26, v80
	v_cvt_f32_f16_sdwa v29, v81 dst_sel:DWORD dst_unused:UNUSED_PAD src0_sel:WORD_1
	v_cvt_f32_f16_sdwa v27, v80 dst_sel:DWORD dst_unused:UNUSED_PAD src0_sel:WORD_1
	v_cvt_f32_f16_e32 v32, v83
	v_cvt_f32_f16_e32 v30, v82
	v_cvt_f32_f16_sdwa v33, v83 dst_sel:DWORD dst_unused:UNUSED_PAD src0_sel:WORD_1
	v_cvt_f32_f16_sdwa v31, v82 dst_sel:DWORD dst_unused:UNUSED_PAD src0_sel:WORD_1
	s_cbranch_vccnz .LBB0_1381
	s_lshl_b64 s[0:1], s[0:1], 11
	s_lshl_b64 s[0:1], s[0:1], 2
	v_readlane_b32 s15, v253, 54
	s_add_u32 s0, s15, s0
	v_readlane_b32 s15, v253, 56
	s_addc_u32 s1, s15, s1
	s_add_u32 s16, s0, 0x1000000
	v_lshlrev_b32_e32 v72, 2, v66
	s_addc_u32 s17, s1, 0
	global_load_dwordx4 v[80:83], v72, s[0:1] offset:16 nt
	global_load_dwordx4 v[84:87], v72, s[0:1] nt
	global_load_dwordx4 v[88:91], v72, s[16:17] nt
	global_load_dwordx4 v[92:95], v72, s[16:17] offset:16 nt
	global_load_dwordx4 v[96:99], v72, s[0:1] offset:2064 nt
	global_load_dwordx4 v[100:103], v72, s[0:1] offset:2048 nt
	global_load_dwordx4 v[104:107], v75, s[16:17] nt
	global_load_dwordx4 v[108:111], v75, s[16:17] offset:16 nt
	global_load_dwordx4 v[112:115], v73, s[0:1] offset:16 nt
	global_load_dwordx4 v[116:119], v73, s[0:1] nt
	global_load_dwordx4 v[120:123], v73, s[16:17] nt
	global_load_dwordx4 v[124:127], v73, s[16:17] offset:16 nt
	global_load_dwordx4 v[128:131], v74, s[0:1] offset:16 nt
	global_load_dwordx4 v[132:135], v74, s[0:1] nt
	global_load_dwordx4 v[136:139], v74, s[16:17] nt
	global_load_dwordx4 v[140:143], v74, s[16:17] offset:16 nt
	s_add_u32 s0, s0, 0x2000000
	s_addc_u32 s1, s1, 0
	global_load_dwordx4 v[144:147], v72, s[0:1] nt
	global_load_dwordx4 v[148:151], v72, s[0:1] offset:16 nt
	global_load_dwordx4 v[152:155], v75, s[0:1] nt
	global_load_dwordx4 v[156:159], v75, s[0:1] offset:16 nt
	global_load_dwordx4 v[160:163], v73, s[0:1] nt
	global_load_dwordx4 v[164:167], v73, s[0:1] offset:16 nt
	global_load_dwordx4 v[168:171], v74, s[0:1] nt
	global_load_dwordx4 v[172:175], v74, s[0:1] offset:16 nt
	s_waitcnt vmcnt(20)
	v_pk_add_f32 v[82:83], v[82:83], v[94:95]
	v_pk_add_f32 v[86:87], v[86:87], v[90:91]
	v_pk_add_f32 v[84:85], v[84:85], v[88:89]
	v_pk_add_f32 v[80:81], v[80:81], v[92:93]
	s_waitcnt vmcnt(17)
	v_pk_add_f32 v[88:89], v[102:103], v[106:107]
	v_pk_add_f32 v[90:91], v[100:101], v[104:105]
	s_waitcnt vmcnt(16)
	v_pk_add_f32 v[92:93], v[98:99], v[110:111]
	v_pk_add_f32 v[94:95], v[96:97], v[108:109]
	s_waitcnt vmcnt(13)
	v_pk_add_f32 v[96:97], v[118:119], v[122:123]
	v_pk_add_f32 v[98:99], v[116:117], v[120:121]
	s_waitcnt vmcnt(12)
	v_pk_add_f32 v[100:101], v[114:115], v[126:127]
	v_pk_add_f32 v[102:103], v[112:113], v[124:125]
	s_waitcnt vmcnt(9)
	v_pk_add_f32 v[104:105], v[134:135], v[138:139]
	v_pk_add_f32 v[106:107], v[132:133], v[136:137]
	s_waitcnt vmcnt(8)
	v_pk_add_f32 v[108:109], v[130:131], v[142:143]
	v_pk_add_f32 v[110:111], v[128:129], v[140:141]
	s_waitcnt vmcnt(7)
	v_pk_add_f32 v[86:87], v[86:87], v[146:147]
	v_pk_add_f32 v[84:85], v[84:85], v[144:145]
	s_waitcnt vmcnt(6)
	v_pk_add_f32 v[82:83], v[82:83], v[150:151]
	v_pk_add_f32 v[80:81], v[80:81], v[148:149]
	s_waitcnt vmcnt(5)
	v_pk_add_f32 v[88:89], v[88:89], v[154:155]
	v_pk_add_f32 v[90:91], v[90:91], v[152:153]
	s_waitcnt vmcnt(4)
	v_pk_add_f32 v[92:93], v[92:93], v[158:159]
	v_pk_add_f32 v[94:95], v[94:95], v[156:157]
	s_waitcnt vmcnt(3)
	v_pk_add_f32 v[96:97], v[96:97], v[162:163]
	v_pk_add_f32 v[98:99], v[98:99], v[160:161]
	s_waitcnt vmcnt(2)
	v_pk_add_f32 v[100:101], v[100:101], v[166:167]
	v_pk_add_f32 v[102:103], v[102:103], v[164:165]
	s_waitcnt vmcnt(1)
	v_pk_add_f32 v[104:105], v[104:105], v[170:171]
	v_pk_add_f32 v[106:107], v[106:107], v[168:169]
	s_waitcnt vmcnt(0)
	v_pk_add_f32 v[108:109], v[108:109], v[174:175]
	v_pk_add_f32 v[110:111], v[110:111], v[172:173]
	v_pk_add_f32 v[4:5], v[86:87], v[4:5]
	v_pk_add_f32 v[2:3], v[84:85], v[2:3]
	v_pk_add_f32 v[8:9], v[82:83], v[8:9]
	v_pk_add_f32 v[6:7], v[80:81], v[6:7]
	v_pk_add_f32 v[12:13], v[88:89], v[12:13]
	v_pk_add_f32 v[10:11], v[90:91], v[10:11]
	v_pk_add_f32 v[16:17], v[92:93], v[16:17]
	v_pk_add_f32 v[14:15], v[94:95], v[14:15]
	v_pk_add_f32 v[20:21], v[96:97], v[20:21]
	v_pk_add_f32 v[18:19], v[98:99], v[18:19]
	v_pk_add_f32 v[24:25], v[100:101], v[24:25]
	v_pk_add_f32 v[22:23], v[102:103], v[22:23]
	v_pk_add_f32 v[28:29], v[104:105], v[28:29]
	v_pk_add_f32 v[26:27], v[106:107], v[26:27]
	v_pk_add_f32 v[32:33], v[108:109], v[32:33]
	v_pk_add_f32 v[30:31], v[110:111], v[30:31]

; #define LAS __attribute__((address_space(3)))
; __device__ __forceinline__ u32x2 f32x4_to_h4(f32x4 v) { return __builtin_bit_cast(u32x2, __builtin_convertvector(v, f16x4)); }
; template <bool COMBINE, bool SRC_F32>
; __device__ __forceinline__ void norm_phase(LAS unsigned char* lds, const void* src_lat, const void* src_ctx, _Float16* xw_ctx, const float* part, int nrows, const float* g, const float* modl, int shift_idx, int scale_idx, bf16* HN, int tid, int lane, int wave) {
;     ...
;         const f32x4 gg = *(const f32x4*)(g + 4 * tid);
;         f32x4 s1[9], s0[9];
; #pragma unroll
;         for (int r = 0; r < 9; ++r) { s1[r] = *(const f32x4*)(modl + (size_t)r * DMODW + scale_idx * D + 4 * tid); s0[r] = *(const f32x4*)(modl + (size_t)r * DMODW + shift_idx * D + 4 * tid); }
; #pragma unroll
;         for (int r = 0; r < 9; ++r) { *(LAS u32x2*)(Gs + r * D + 4 * tid) = f32x4_to_h4(gg * (1.0f + s1[r])); *(LAS u32x2*)(Ss + r * D + 4 * tid) = f32x4_to_h4(s0[r]); }
.LBB0_1762:
	s_cmp_lt_i32 s90, 15
	s_cselect_b64 s[2:3], -1, 0
	s_and_b64 s[0:1], s[2:3], s[0:1]
	s_andn2_b64 vcc, exec, s[0:1]
	s_cbranch_vccnz .LBB0_1775
	v_readlane_b32 s8, v253, 10
	s_waitcnt vmcnt(0)
	v_lshlrev_b32_e32 v34, 4, v0
	v_mov_b32_e32 v35, 0
	v_readlane_b32 s20, v253, 22
	v_readlane_b32 s21, v253, 23
	v_lshl_add_u64 v[76:77], s[88:89], 0, v[34:35]
	s_lshl_b32 s0, s86, 3
	v_lshl_add_u64 v[2:3], s[20:21], 0, v[34:35]
	v_add_co_u32_e32 v2, vcc, 0x8000, v2
	s_add_i32 s0, s96, s0
	s_nop 0
	v_addc_co_u32_e32 v3, vcc, 0, v3, vcc
	v_add_co_u32_e32 v6, vcc, 0x1aa000, v76
	global_load_dwordx4 v[2:5], v[2:3], off
	s_nop 0
	v_addc_co_u32_e32 v7, vcc, 0, v77, vcc
	v_add_co_u32_e32 v10, vcc, 0x1a8000, v76
	v_add_u32_e32 v34, 0x9000, v228
	s_nop 0
	v_addc_co_u32_e32 v11, vcc, 0, v77, vcc
	v_add_co_u32_e32 v14, vcc, 0x1bc000, v76
	global_load_dwordx4 v[6:9], v[6:7], off
	s_nop 0
	global_load_dwordx4 v[10:13], v[10:11], off
	v_addc_co_u32_e32 v15, vcc, 0, v77, vcc
	v_add_co_u32_e32 v18, vcc, 0x1ba000, v76
	s_cmpk_lt_i32 s0, 0x4800
	s_nop 0
	v_addc_co_u32_e32 v19, vcc, 0, v77, vcc
	v_add_co_u32_e32 v22, vcc, 0x1ce000, v76
	global_load_dwordx4 v[14:17], v[14:15], off
	s_nop 0
	global_load_dwordx4 v[18:21], v[18:19], off
	v_addc_co_u32_e32 v23, vcc, 0, v77, vcc
	v_add_co_u32_e32 v26, vcc, 0x1cc000, v76
	s_cselect_b64 s[4:5], -1, 0
	s_nop 0
	v_addc_co_u32_e32 v27, vcc, 0, v77, vcc
	v_add_co_u32_e32 v30, vcc, 0x1e0000, v76
	global_load_dwordx4 v[22:25], v[22:23], off
	s_nop 0
	global_load_dwordx4 v[26:29], v[26:27], off
	v_addc_co_u32_e32 v31, vcc, 0, v77, vcc
	v_add_co_u32_e32 v36, vcc, 0x1de000, v76
	s_cmpk_gt_i32 s0, 0x47ff
	s_nop 0
	v_addc_co_u32_e32 v37, vcc, 0, v77, vcc
	v_add_co_u32_e32 v40, vcc, 0x1f2000, v76
	global_load_dwordx4 v[30:33], v[30:31], off
	s_nop 0
	global_load_dwordx4 v[36:39], v[36:37], off
	v_addc_co_u32_e32 v41, vcc, 0, v77, vcc
	v_add_co_u32_e32 v44, vcc, 0x1f0000, v76
	v_readlane_b32 s9, v253, 11
	s_nop 0
	v_addc_co_u32_e32 v45, vcc, 0, v77, vcc
	v_add_co_u32_e32 v48, vcc, 0x204000, v76
	global_load_dwordx4 v[40:43], v[40:41], off
	s_nop 0
	global_load_dwordx4 v[44:47], v[44:45], off
	v_addc_co_u32_e32 v49, vcc, 0, v77, vcc
	v_add_co_u32_e32 v52, vcc, 0x202000, v76
	v_readlane_b32 s10, v253, 12
	s_nop 0
	v_addc_co_u32_e32 v53, vcc, 0, v77, vcc
	v_add_co_u32_e32 v56, vcc, 0x216000, v76
	global_load_dwordx4 v[48:51], v[48:49], off
	s_nop 0
	global_load_dwordx4 v[52:55], v[52:53], off
	v_addc_co_u32_e32 v57, vcc, 0, v77, vcc
	v_add_co_u32_e32 v60, vcc, 0x214000, v76
	v_readlane_b32 s11, v253, 13
	s_nop 0
	v_addc_co_u32_e32 v61, vcc, 0, v77, vcc
	v_add_co_u32_e32 v64, vcc, 0x228000, v76
	global_load_dwordx4 v[56:59], v[56:57], off
	s_nop 0
	global_load_dwordx4 v[60:63], v[60:61], off
	v_addc_co_u32_e32 v65, vcc, 0, v77, vcc
	v_add_co_u32_e32 v68, vcc, 0x226000, v76
	global_load_dwordx4 v[64:67], v[64:65], off
	s_nop 0
	v_addc_co_u32_e32 v69, vcc, 0, v77, vcc
	v_add_co_u32_e32 v72, vcc, 0x23a000, v76
	global_load_dwordx4 v[68:71], v[68:69], off
	s_nop 0
	v_addc_co_u32_e32 v73, vcc, 0, v77, vcc
	global_load_dwordx4 v[72:75], v[72:73], off
	v_add_co_u32_e32 v76, vcc, 0x238000, v76
	v_readlane_b32 s12, v253, 14
	s_nop 0
	v_addc_co_u32_e32 v77, vcc, 0, v77, vcc
	global_load_dwordx4 v[76:79], v[76:77], off
	s_waitcnt vmcnt(17)
	v_pk_add_f32 v[8:9], v[8:9], 1.0 op_sel_hi:[1,0]
	v_pk_add_f32 v[6:7], v[6:7], 1.0 op_sel_hi:[1,0]
	v_pk_mul_f32 v[8:9], v[4:5], v[8:9]
	v_pk_mul_f32 v[6:7], v[2:3], v[6:7]
	v_cvt_pk_f16_f32 v9, v8, v9
	v_cvt_pk_f16_f32 v8, v6, v7
	s_waitcnt vmcnt(16)
	v_cvt_pk_f16_f32 v7, v12, v13
	v_cvt_pk_f16_f32 v6, v10, v11
	v_readlane_b32 s13, v253, 15
	s_waitcnt vmcnt(15)
	v_pk_add_f32 v[10:11], v[16:17], 1.0 op_sel_hi:[1,0]
	v_pk_add_f32 v[12:13], v[14:15], 1.0 op_sel_hi:[1,0]
	v_pk_mul_f32 v[10:11], v[4:5], v[10:11]
	v_pk_mul_f32 v[12:13], v[2:3], v[12:13]
	v_cvt_pk_f16_f32 v11, v10, v11
	v_cvt_pk_f16_f32 v10, v12, v13
	ds_write2st64_b64 v228, v[8:9], v[10:11] offset1:8
	s_waitcnt vmcnt(14)
	v_cvt_pk_f16_f32 v9, v20, v21
	v_cvt_pk_f16_f32 v8, v18, v19
	v_readlane_b32 s14, v253, 16
	s_waitcnt vmcnt(13)
	v_pk_add_f32 v[10:11], v[24:25], 1.0 op_sel_hi:[1,0]
	v_pk_add_f32 v[12:13], v[22:23], 1.0 op_sel_hi:[1,0]
	v_pk_mul_f32 v[10:11], v[4:5], v[10:11]
	v_pk_mul_f32 v[12:13], v[2:3], v[12:13]
	v_cvt_pk_f16_f32 v11, v10, v11
	v_cvt_pk_f16_f32 v10, v12, v13
	s_waitcnt vmcnt(12)
	v_cvt_pk_f16_f32 v13, v28, v29
	v_cvt_pk_f16_f32 v12, v26, v27
	ds_write2st64_b64 v228, v[8:9], v[12:13] offset0:80 offset1:88
	v_readlane_b32 s15, v253, 17
	s_waitcnt vmcnt(11)
	v_pk_add_f32 v[8:9], v[32:33], 1.0 op_sel_hi:[1,0]
	v_pk_add_f32 v[12:13], v[30:31], 1.0 op_sel_hi:[1,0]
	v_pk_mul_f32 v[8:9], v[4:5], v[8:9]
	v_pk_mul_f32 v[12:13], v[2:3], v[12:13]
	v_cvt_pk_f16_f32 v9, v8, v9
	v_cvt_pk_f16_f32 v8, v12, v13
	ds_write2st64_b64 v228, v[10:11], v[8:9] offset0:16 offset1:24
	s_waitcnt vmcnt(10)
	v_cvt_pk_f16_f32 v9, v38, v39
	v_cvt_pk_f16_f32 v8, v36, v37
	v_mov_b32_e32 v36, v35
	s_waitcnt vmcnt(9)
	v_pk_add_f32 v[10:11], v[42:43], 1.0 op_sel_hi:[1,0]
	v_pk_add_f32 v[12:13], v[40:41], 1.0 op_sel_hi:[1,0]
	v_pk_mul_f32 v[10:11], v[4:5], v[10:11]
	v_pk_mul_f32 v[12:13], v[2:3], v[12:13]
	v_cvt_pk_f16_f32 v11, v10, v11
	v_cvt_pk_f16_f32 v10, v12, v13
	s_waitcnt vmcnt(8)
	v_cvt_pk_f16_f32 v13, v46, v47
	v_cvt_pk_f16_f32 v12, v44, v45
	ds_write2st64_b64 v228, v[8:9], v[12:13] offset0:96 offset1:104
	v_mov_b32_e32 v37, v35
	s_waitcnt vmcnt(7)
	v_pk_add_f32 v[8:9], v[50:51], 1.0 op_sel_hi:[1,0]
	v_pk_add_f32 v[12:13], v[48:49], 1.0 op_sel_hi:[1,0]
	v_pk_mul_f32 v[8:9], v[4:5], v[8:9]
	v_pk_mul_f32 v[12:13], v[2:3], v[12:13]
	v_cvt_pk_f16_f32 v9, v8, v9
	v_cvt_pk_f16_f32 v8, v12, v13
	ds_write2st64_b64 v228, v[10:11], v[8:9] offset0:32 offset1:40
	s_waitcnt vmcnt(6)
; #define LAS __attribute__((address_space(3)))
; __device__ __forceinline__ u32x2 f32x4_to_h4(f32x4 v) { return __builtin_bit_cast(u32x2, __builtin_convertvector(v, f16x4)); }
; template <bool COMBINE, bool SRC_F32>
; __device__ __forceinline__ void norm_phase(LAS unsigned char* lds, const void* src_lat, const void* src_ctx, _Float16* xw_ctx, const float* part, int nrows, const float* g, const float* modl, int shift_idx, int scale_idx, bf16* HN, int tid, int lane, int wave) {
;     ...
;         for (int r = 0; r < 9; ++r) { *(LAS u32x2*)(Gs + r * D + 4 * tid) = f32x4_to_h4(gg * (1.0f + s1[r])); *(LAS u32x2*)(Ss + r * D + 4 * tid) = f32x4_to_h4(s0[r]); }
;     ...
;     if (gw < nrows) NORM_LOAD(v, gw);
	v_cvt_pk_f16_f32 v9, v54, v55
	v_cvt_pk_f16_f32 v8, v52, v53
	v_mov_b32_e32 v38, v35
	s_waitcnt vmcnt(5)
	v_pk_add_f32 v[10:11], v[58:59], 1.0 op_sel_hi:[1,0]
	v_pk_add_f32 v[12:13], v[56:57], 1.0 op_sel_hi:[1,0]
	v_pk_mul_f32 v[10:11], v[4:5], v[10:11]
	v_pk_mul_f32 v[12:13], v[2:3], v[12:13]
	v_cvt_pk_f16_f32 v11, v10, v11
	v_cvt_pk_f16_f32 v10, v12, v13
	s_waitcnt vmcnt(4)
	v_cvt_pk_f16_f32 v13, v62, v63
	v_cvt_pk_f16_f32 v12, v60, v61
	ds_write2st64_b64 v228, v[8:9], v[12:13] offset0:112 offset1:120
	s_waitcnt vmcnt(3)
	v_pk_add_f32 v[8:9], v[66:67], 1.0 op_sel_hi:[1,0]
	v_pk_add_f32 v[12:13], v[64:65], 1.0 op_sel_hi:[1,0]
	v_pk_mul_f32 v[8:9], v[4:5], v[8:9]
	v_pk_mul_f32 v[12:13], v[2:3], v[12:13]
	v_cvt_pk_f16_f32 v9, v8, v9
	v_cvt_pk_f16_f32 v8, v12, v13
	ds_write2st64_b64 v228, v[10:11], v[8:9] offset0:48 offset1:56
	s_waitcnt vmcnt(1)
	v_pk_add_f32 v[10:11], v[74:75], 1.0 op_sel_hi:[1,0]
	v_pk_add_f32 v[12:13], v[72:73], 1.0 op_sel_hi:[1,0]
	v_pk_mul_f32 v[4:5], v[4:5], v[10:11]
	v_pk_mul_f32 v[2:3], v[2:3], v[12:13]
	v_cvt_pk_f16_f32 v9, v70, v71
	v_cvt_pk_f16_f32 v8, v68, v69
	v_cvt_pk_f16_f32 v5, v4, v5
	v_cvt_pk_f16_f32 v4, v2, v3
	s_waitcnt vmcnt(0)
	v_cvt_pk_f16_f32 v3, v78, v79
	v_cvt_pk_f16_f32 v2, v76, v77
	ds_write2st64_b64 v34, v[8:9], v[2:3] offset0:56 offset1:64
	v_mov_b32_e32 v34, v35
	v_mov_b32_e32 v39, v35
	v_mov_b32_e32 v40, v35
	v_mov_b32_e32 v41, v35
	v_mov_b32_e32 v42, v35
	v_mov_b32_e32 v43, v35
	v_mov_b32_e32 v44, v35
	v_mov_b32_e32 v45, v35
	v_mov_b32_e32 v46, v35
	v_mov_b32_e32 v47, v35
	v_mov_b32_e32 v48, v35
	v_mov_b32_e32 v49, v35
	v_mov_b32_e32 v50, v35
	v_mov_b32_e32 v51, v35
	v_mov_b32_e32 v52, v35
	v_mov_b32_e32 v53, v35
	v_mov_b32_e32 v54, v35
	v_mov_b32_e32 v55, v35
	v_mov_b32_e32 v56, v35
	v_mov_b32_e32 v57, v35
	v_mov_b32_e32 v58, v35
	v_mov_b32_e32 v59, v35
	v_mov_b32_e32 v60, v35
	v_mov_b32_e32 v61, v35
	v_mov_b32_e32 v62, v35
	v_mov_b32_e32 v63, v35
	v_mov_b32_e32 v64, v35
	v_mov_b32_e32 v65, v35
	v_readlane_b32 s16, v253, 18
	v_readlane_b32 s17, v253, 19
	v_readlane_b32 s18, v253, 20
	v_readlane_b32 s19, v253, 21
	v_readlane_b32 s22, v253, 24
	v_readlane_b32 s23, v253, 25
	ds_write2st64_b64 v228, v[4:5], v[6:7] offset0:64 offset1:72
	s_cbranch_scc1 .LBB0_1766
	s_ashr_i32 s1, s0, 31
	s_add_i32 s10, s0, 0xffffc000
	s_cmpk_lt_i32 s0, 0x4000
	s_cselect_b64 s[8:9], -1, 0
	s_and_b64 vcc, s[8:9], exec
	v_readlane_b32 s8, v253, 52
	v_readlane_b32 s9, v253, 53
	s_cselect_b32 s12, s9, s7
	s_cselect_b32 s13, s8, s6
	s_cselect_b32 s9, s1, 0
	s_cselect_b32 s8, s0, s10
	s_lshl_b64 s[10:11], s[8:9], 12
	s_add_u32 s10, s13, s10
	s_addc_u32 s11, s12, s11
	v_lshlrev_b32_e32 v14, 4, v1
	global_load_dwordx4 v[2:5], v14, s[10:11] nt
	global_load_dwordx4 v[6:9], v14, s[10:11] offset:1024 nt
	global_load_dwordx4 v[10:13], v14, s[10:11] offset:2048 nt
	s_nop 0
	global_load_dwordx4 v[14:17], v14, s[10:11] offset:3072 nt
	s_waitcnt vmcnt(3)
	v_cvt_f32_f16_e32 v36, v3
	v_cvt_f32_f16_e32 v34, v2
	v_cvt_f32_f16_sdwa v37, v3 dst_sel:DWORD dst_unused:UNUSED_PAD src0_sel:WORD_1
	v_cvt_f32_f16_sdwa v35, v2 dst_sel:DWORD dst_unused:UNUSED_PAD src0_sel:WORD_1
	v_cvt_f32_f16_e32 v40, v5
	v_cvt_f32_f16_e32 v38, v4
	v_cvt_f32_f16_sdwa v41, v5 dst_sel:DWORD dst_unused:UNUSED_PAD src0_sel:WORD_1
	v_cvt_f32_f16_sdwa v39, v4 dst_sel:DWORD dst_unused:UNUSED_PAD src0_sel:WORD_1
	s_waitcnt vmcnt(2)
	v_cvt_f32_f16_e32 v44, v7
	v_cvt_f32_f16_e32 v42, v6
	v_cvt_f32_f16_sdwa v45, v7 dst_sel:DWORD dst_unused:UNUSED_PAD src0_sel:WORD_1
	v_cvt_f32_f16_sdwa v43, v6 dst_sel:DWORD dst_unused:UNUSED_PAD src0_sel:WORD_1
	v_cvt_f32_f16_e32 v48, v9
	v_cvt_f32_f16_e32 v46, v8
	v_cvt_f32_f16_sdwa v49, v9 dst_sel:DWORD dst_unused:UNUSED_PAD src0_sel:WORD_1
	v_cvt_f32_f16_sdwa v47, v8 dst_sel:DWORD dst_unused:UNUSED_PAD src0_sel:WORD_1
	s_waitcnt vmcnt(1)
	v_cvt_f32_f16_e32 v52, v11
	v_cvt_f32_f16_e32 v50, v10
	v_cvt_f32_f16_sdwa v53, v11 dst_sel:DWORD dst_unused:UNUSED_PAD src0_sel:WORD_1
	v_cvt_f32_f16_sdwa v51, v10 dst_sel:DWORD dst_unused:UNUSED_PAD src0_sel:WORD_1
	v_cvt_f32_f16_e32 v56, v13
	v_cvt_f32_f16_e32 v54, v12
	v_cvt_f32_f16_sdwa v57, v13 dst_sel:DWORD dst_unused:UNUSED_PAD src0_sel:WORD_1
	v_cvt_f32_f16_sdwa v55, v12 dst_sel:DWORD dst_unused:UNUSED_PAD src0_sel:WORD_1
	s_waitcnt vmcnt(0)
	v_cvt_f32_f16_e32 v60, v15
	v_cvt_f32_f16_e32 v58, v14
	v_cvt_f32_f16_sdwa v61, v15 dst_sel:DWORD dst_unused:UNUSED_PAD src0_sel:WORD_1
	v_cvt_f32_f16_sdwa v59, v14 dst_sel:DWORD dst_unused:UNUSED_PAD src0_sel:WORD_1
	v_cvt_f32_f16_e32 v64, v17
	v_cvt_f32_f16_e32 v62, v16
	v_cvt_f32_f16_sdwa v65, v17 dst_sel:DWORD dst_unused:UNUSED_PAD src0_sel:WORD_1
	v_cvt_f32_f16_sdwa v63, v16 dst_sel:DWORD dst_unused:UNUSED_PAD src0_sel:WORD_1
	s_cbranch_vccnz .LBB0_1766
	s_lshl_b64 s[8:9], s[8:9], 11
	s_lshl_b64 s[8:9], s[8:9], 2
	v_readlane_b32 s1, v253, 54
	s_add_u32 s8, s1, s8
	v_readlane_b32 s1, v253, 56
	v_lshlrev_b32_e32 v2, 3, v1
	s_addc_u32 s9, s1, s9
	v_lshlrev_b32_e32 v102, 2, v2
	s_add_u32 s10, s8, 0x1000000
	s_addc_u32 s11, s9, 0
	v_or_b32_e32 v110, 0x800, v102
	v_or_b32_e32 v126, 0x1800, v102
	global_load_dwordx4 v[2:5], v102, s[8:9] offset:16 nt
	global_load_dwordx4 v[6:9], v102, s[8:9] nt
	global_load_dwordx4 v[10:13], v102, s[8:9] offset:2064 nt
	global_load_dwordx4 v[14:17], v102, s[8:9] offset:2048 nt
	global_load_dwordx4 v[18:21], v102, s[10:11] offset:16 nt
	global_load_dwordx4 v[22:25], v102, s[10:11] nt
	v_or_b32_e32 v118, 0x1000, v102
	global_load_dwordx4 v[26:29], v110, s[10:11] offset:16 nt
	global_load_dwordx4 v[30:33], v110, s[10:11] nt
	global_load_dwordx4 v[66:69], v118, s[8:9] offset:16 nt
	global_load_dwordx4 v[70:73], v118, s[8:9] nt
	global_load_dwordx4 v[74:77], v118, s[10:11] offset:16 nt
	global_load_dwordx4 v[78:81], v118, s[10:11] nt
	global_load_dwordx4 v[82:85], v126, s[8:9] offset:16 nt
	global_load_dwordx4 v[86:89], v126, s[8:9] nt
	global_load_dwordx4 v[90:93], v126, s[10:11] nt
	global_load_dwordx4 v[94:97], v126, s[10:11] offset:16 nt
	s_add_u32 s8, s8, 0x2000000
	s_addc_u32 s9, s9, 0
	global_load_dwordx4 v[98:101], v102, s[8:9] nt
	s_nop 0
	global_load_dwordx4 v[102:105], v102, s[8:9] offset:16 nt
	s_nop 0
	global_load_dwordx4 v[106:109], v110, s[8:9] nt
	s_nop 0
	global_load_dwordx4 v[110:113], v110, s[8:9] offset:16 nt
	s_nop 0
	global_load_dwordx4 v[114:117], v118, s[8:9] nt
	s_nop 0
	global_load_dwordx4 v[118:121], v118, s[8:9] offset:16 nt
	s_nop 0
	global_load_dwordx4 v[122:125], v126, s[8:9] nt
	s_nop 0
	global_load_dwordx4 v[126:129], v126, s[8:9] offset:16 nt
	s_waitcnt vmcnt(17)
	v_pk_add_f32 v[12:13], v[12:13], v[28:29]
	v_pk_add_f32 v[4:5], v[4:5], v[20:21]
	v_pk_add_f32 v[8:9], v[8:9], v[24:25]
	v_pk_add_f32 v[6:7], v[6:7], v[22:23]
	v_pk_add_f32 v[2:3], v[2:3], v[18:19]
	s_waitcnt vmcnt(16)
	v_pk_add_f32 v[16:17], v[16:17], v[32:33]
	v_pk_add_f32 v[14:15], v[14:15], v[30:31]
	v_pk_add_f32 v[10:11], v[10:11], v[26:27]
	s_waitcnt vmcnt(12)
	v_pk_add_f32 v[18:19], v[72:73], v[80:81]
	v_pk_add_f32 v[20:21], v[70:71], v[78:79]
	v_pk_add_f32 v[22:23], v[68:69], v[76:77]
	v_pk_add_f32 v[24:25], v[66:67], v[74:75]
	s_waitcnt vmcnt(9)
	v_pk_add_f32 v[26:27], v[88:89], v[92:93]
	v_pk_add_f32 v[28:29], v[86:87], v[90:91]
	s_waitcnt vmcnt(8)
	v_pk_add_f32 v[30:31], v[84:85], v[96:97]
	v_pk_add_f32 v[32:33], v[82:83], v[94:95]
	s_waitcnt vmcnt(7)
	v_pk_add_f32 v[8:9], v[8:9], v[100:101]
	v_pk_add_f32 v[6:7], v[6:7], v[98:99]
	s_waitcnt vmcnt(6)
	v_pk_add_f32 v[4:5], v[4:5], v[104:105]
	v_pk_add_f32 v[2:3], v[2:3], v[102:103]
	s_waitcnt vmcnt(5)
	v_pk_add_f32 v[16:17], v[16:17], v[108:109]
	v_pk_add_f32 v[14:15], v[14:15], v[106:107]
	s_waitcnt vmcnt(4)
	v_pk_add_f32 v[12:13], v[12:13], v[112:113]
	v_pk_add_f32 v[10:11], v[10:11], v[110:111]
	s_waitcnt vmcnt(3)
	v_pk_add_f32 v[18:19], v[18:19], v[116:117]
	v_pk_add_f32 v[20:21], v[20:21], v[114:115]
	s_waitcnt vmcnt(2)
	v_pk_add_f32 v[22:23], v[22:23], v[120:121]
	v_pk_add_f32 v[24:25], v[24:25], v[118:119]
	s_waitcnt vmcnt(1)
	v_pk_add_f32 v[26:27], v[26:27], v[124:125]
	v_pk_add_f32 v[28:29], v[28:29], v[122:123]
	s_waitcnt vmcnt(0)
	v_pk_add_f32 v[30:31], v[30:31], v[128:129]
	v_pk_add_f32 v[32:33], v[32:33], v[126:127]
	v_pk_add_f32 v[36:37], v[8:9], v[36:37]
	v_pk_add_f32 v[34:35], v[6:7], v[34:35]
	v_pk_add_f32 v[40:41], v[4:5], v[40:41]
	v_pk_add_f32 v[38:39], v[2:3], v[38:39]
	v_pk_add_f32 v[44:45], v[16:17], v[44:45]
	v_pk_add_f32 v[42:43], v[14:15], v[42:43]
	v_pk_add_f32 v[48:49], v[12:13], v[48:49]
	v_pk_add_f32 v[46:47], v[10:11], v[46:47]
	v_pk_add_f32 v[52:53], v[18:19], v[52:53]
	v_pk_add_f32 v[50:51], v[20:21], v[50:51]
	v_pk_add_f32 v[56:57], v[22:23], v[56:57]
	v_pk_add_f32 v[54:55], v[24:25], v[54:55]
	v_pk_add_f32 v[60:61], v[26:27], v[60:61]
	v_pk_add_f32 v[58:59], v[28:29], v[58:59]
	v_pk_add_f32 v[64:65], v[30:31], v[64:65]
	v_pk_add_f32 v[62:63], v[32:33], v[62:63]

; #define LAS __attribute__((address_space(3)))
; __device__ __forceinline__ u32x2 f32x4_to_h4(f32x4 v) { return __builtin_bit_cast(u32x2, __builtin_convertvector(v, f16x4)); }
; template <bool COMBINE, bool SRC_F32>
; __device__ __forceinline__ void norm_phase(LAS unsigned char* lds, const void* src_lat, const void* src_ctx, _Float16* xw_ctx, const float* part, int nrows, const float* g, const float* modl, int shift_idx, int scale_idx, bf16* HN, int tid, int lane, int wave) {
;     ...
;         const f32x4 gg = *(const f32x4*)(g + 4 * tid);
;         f32x4 s1[9], s0[9];
; #pragma unroll
;         for (int r = 0; r < 9; ++r) { s1[r] = *(const f32x4*)(modl + (size_t)r * DMODW + scale_idx * D + 4 * tid); s0[r] = *(const f32x4*)(modl + (size_t)r * DMODW + shift_idx * D + 4 * tid); }
; #pragma unroll
;         for (int r = 0; r < 9; ++r) { *(LAS u32x2*)(Gs + r * D + 4 * tid) = f32x4_to_h4(gg * (1.0f + s1[r])); *(LAS u32x2*)(Ss + r * D + 4 * tid) = f32x4_to_h4(s0[r]); }
.LBB0_2360:
	s_cmp_lt_i32 s90, 19
	s_cselect_b64 s[2:3], -1, 0
	s_and_b64 s[0:1], s[2:3], s[0:1]
	s_andn2_b64 vcc, exec, s[0:1]
	s_cbranch_vccnz .LBB0_2369
	v_readlane_b32 s4, v253, 10
	s_waitcnt vmcnt(0)
	v_lshlrev_b32_e32 v34, 4, v0
	v_mov_b32_e32 v35, 0
	v_readlane_b32 s16, v253, 22
	v_readlane_b32 s17, v253, 23
	v_lshl_add_u64 v[76:77], s[88:89], 0, v[34:35]
	s_lshl_b32 s0, s86, 3
	v_lshl_add_u64 v[2:3], s[16:17], 0, v[34:35]
	v_add_co_u32_e32 v2, vcc, 0xa000, v2
	v_readlane_b32 s8, v253, 14
	s_nop 0
	v_addc_co_u32_e32 v3, vcc, 0, v3, vcc
	v_add_co_u32_e32 v14, vcc, 0x1b0000, v76
	global_load_dwordx4 v[2:5], v[2:3], off
	s_nop 0
	v_addc_co_u32_e32 v15, vcc, 0, v77, vcc
	v_add_co_u32_e32 v16, vcc, 0x1ae000, v76
	s_add_i32 s8, s96, s0
	s_nop 0
	v_addc_co_u32_e32 v17, vcc, 0, v77, vcc
	v_add_co_u32_e32 v22, vcc, 0x1c2000, v76
	global_load_dwordx4 v[6:9], v[14:15], off
	global_load_dwordx4 v[10:13], v[16:17], off
	v_addc_co_u32_e32 v23, vcc, 0, v77, vcc
	v_add_co_u32_e32 v24, vcc, 0x1c0000, v76
	v_add_u32_e32 v34, 0x9000, v228
	s_nop 0
	v_addc_co_u32_e32 v25, vcc, 0, v77, vcc
	v_add_co_u32_e32 v30, vcc, 0x1d4000, v76
	global_load_dwordx4 v[14:17], v[22:23], off
	global_load_dwordx4 v[18:21], v[24:25], off
	v_addc_co_u32_e32 v31, vcc, 0, v77, vcc
	v_add_co_u32_e32 v32, vcc, 0x1d2000, v76
	s_cmpk_lt_i32 s8, 0x4000
	s_nop 0
	v_addc_co_u32_e32 v33, vcc, 0, v77, vcc
	v_add_co_u32_e32 v40, vcc, 0x1e6000, v76
	global_load_dwordx4 v[22:25], v[30:31], off
	global_load_dwordx4 v[26:29], v[32:33], off
	v_addc_co_u32_e32 v41, vcc, 0, v77, vcc
	v_add_co_u32_e32 v42, vcc, 0x1e4000, v76
	s_cselect_b64 s[0:1], -1, 0
	s_nop 0
	v_addc_co_u32_e32 v43, vcc, 0, v77, vcc
	v_add_co_u32_e32 v48, vcc, 0x1f8000, v76
	global_load_dwordx4 v[30:33], v[40:41], off
	global_load_dwordx4 v[36:39], v[42:43], off
	v_addc_co_u32_e32 v49, vcc, 0, v77, vcc
	v_add_co_u32_e32 v50, vcc, 0x1f6000, v76
	s_cmpk_gt_i32 s8, 0x3fff
	s_nop 0
	v_addc_co_u32_e32 v51, vcc, 0, v77, vcc
	v_add_co_u32_e32 v56, vcc, 0x20a000, v76
	global_load_dwordx4 v[40:43], v[48:49], off
	global_load_dwordx4 v[44:47], v[50:51], off
	v_addc_co_u32_e32 v57, vcc, 0, v77, vcc
	v_add_co_u32_e32 v58, vcc, 0x208000, v76
	v_readlane_b32 s5, v253, 11
	s_nop 0
	v_addc_co_u32_e32 v59, vcc, 0, v77, vcc
	v_add_co_u32_e32 v64, vcc, 0x21c000, v76
	global_load_dwordx4 v[48:51], v[56:57], off
	global_load_dwordx4 v[52:55], v[58:59], off
	v_addc_co_u32_e32 v65, vcc, 0, v77, vcc
	v_add_co_u32_e32 v66, vcc, 0x21a000, v76
	v_readlane_b32 s6, v253, 12
	s_nop 0
	v_addc_co_u32_e32 v67, vcc, 0, v77, vcc
	global_load_dwordx4 v[56:59], v[64:65], off
	global_load_dwordx4 v[60:63], v[66:67], off
	v_add_co_u32_e32 v64, vcc, 0x22e000, v76
	v_readlane_b32 s7, v253, 13
	s_nop 0
	v_addc_co_u32_e32 v65, vcc, 0, v77, vcc
	v_add_co_u32_e32 v68, vcc, 0x22c000, v76
	global_load_dwordx4 v[64:67], v[64:65], off
	s_nop 0
	v_addc_co_u32_e32 v69, vcc, 0, v77, vcc
	v_add_co_u32_e32 v72, vcc, 0x240000, v76
	global_load_dwordx4 v[68:71], v[68:69], off
	s_nop 0
	v_addc_co_u32_e32 v73, vcc, 0, v77, vcc
	global_load_dwordx4 v[72:75], v[72:73], off
	v_add_co_u32_e32 v76, vcc, 0x23e000, v76
	v_readlane_b32 s9, v253, 15
	s_nop 0
	v_addc_co_u32_e32 v77, vcc, 0, v77, vcc
	global_load_dwordx4 v[76:79], v[76:77], off
	s_waitcnt vmcnt(17)
	v_pk_add_f32 v[8:9], v[8:9], 1.0 op_sel_hi:[1,0]
	v_pk_add_f32 v[6:7], v[6:7], 1.0 op_sel_hi:[1,0]
	v_pk_mul_f32 v[8:9], v[4:5], v[8:9]
	v_pk_mul_f32 v[6:7], v[2:3], v[6:7]
	v_cvt_pk_f16_f32 v9, v8, v9
	v_cvt_pk_f16_f32 v8, v6, v7
	s_waitcnt vmcnt(16)
	v_cvt_pk_f16_f32 v7, v12, v13
	v_cvt_pk_f16_f32 v6, v10, v11
	s_waitcnt vmcnt(15)
	v_pk_add_f32 v[10:11], v[16:17], 1.0 op_sel_hi:[1,0]
	v_pk_add_f32 v[12:13], v[14:15], 1.0 op_sel_hi:[1,0]
	v_pk_mul_f32 v[10:11], v[4:5], v[10:11]
	v_pk_mul_f32 v[12:13], v[2:3], v[12:13]
	v_cvt_pk_f16_f32 v11, v10, v11
	v_cvt_pk_f16_f32 v10, v12, v13
	ds_write2st64_b64 v228, v[8:9], v[10:11] offset1:8
	s_waitcnt vmcnt(14)
	v_cvt_pk_f16_f32 v9, v20, v21
	v_cvt_pk_f16_f32 v8, v18, v19
	v_readlane_b32 s10, v253, 16
	s_waitcnt vmcnt(13)
	v_pk_add_f32 v[10:11], v[24:25], 1.0 op_sel_hi:[1,0]
	v_pk_add_f32 v[12:13], v[22:23], 1.0 op_sel_hi:[1,0]
	v_pk_mul_f32 v[10:11], v[4:5], v[10:11]
	v_pk_mul_f32 v[12:13], v[2:3], v[12:13]
	v_cvt_pk_f16_f32 v11, v10, v11
	v_cvt_pk_f16_f32 v10, v12, v13
	s_waitcnt vmcnt(12)
	v_cvt_pk_f16_f32 v13, v28, v29
	v_cvt_pk_f16_f32 v12, v26, v27
	ds_write2st64_b64 v228, v[8:9], v[12:13] offset0:80 offset1:88
	v_readlane_b32 s11, v253, 17
	s_waitcnt vmcnt(11)
	v_pk_add_f32 v[8:9], v[32:33], 1.0 op_sel_hi:[1,0]
	v_pk_add_f32 v[12:13], v[30:31], 1.0 op_sel_hi:[1,0]
	v_pk_mul_f32 v[8:9], v[4:5], v[8:9]
	v_pk_mul_f32 v[12:13], v[2:3], v[12:13]
	v_cvt_pk_f16_f32 v9, v8, v9
	v_cvt_pk_f16_f32 v8, v12, v13
	ds_write2st64_b64 v228, v[10:11], v[8:9] offset0:16 offset1:24
	s_waitcnt vmcnt(10)
	v_cvt_pk_f16_f32 v9, v38, v39
	v_cvt_pk_f16_f32 v8, v36, v37
	v_readlane_b32 s12, v253, 18
	s_waitcnt vmcnt(9)
	v_pk_add_f32 v[10:11], v[42:43], 1.0 op_sel_hi:[1,0]
	v_pk_add_f32 v[12:13], v[40:41], 1.0 op_sel_hi:[1,0]
	v_pk_mul_f32 v[10:11], v[4:5], v[10:11]
	v_pk_mul_f32 v[12:13], v[2:3], v[12:13]
	v_cvt_pk_f16_f32 v11, v10, v11
	v_cvt_pk_f16_f32 v10, v12, v13
	s_waitcnt vmcnt(8)
; #define LAS __attribute__((address_space(3)))
; __device__ __forceinline__ u32x2 f32x4_to_h4(f32x4 v) { return __builtin_bit_cast(u32x2, __builtin_convertvector(v, f16x4)); }
; template <bool COMBINE, bool SRC_F32>
; __device__ __forceinline__ void norm_phase(LAS unsigned char* lds, const void* src_lat, const void* src_ctx, _Float16* xw_ctx, const float* part, int nrows, const float* g, const float* modl, int shift_idx, int scale_idx, bf16* HN, int tid, int lane, int wave) {
;     ...
;         for (int r = 0; r < 9; ++r) { *(LAS u32x2*)(Gs + r * D + 4 * tid) = f32x4_to_h4(gg * (1.0f + s1[r])); *(LAS u32x2*)(Ss + r * D + 4 * tid) = f32x4_to_h4(s0[r]); }
;     ...
;     if (gw < nrows) NORM_LOAD(v, gw);
	v_cvt_pk_f16_f32 v13, v46, v47
	v_cvt_pk_f16_f32 v12, v44, v45
	ds_write2st64_b64 v228, v[8:9], v[12:13] offset0:96 offset1:104
	v_mov_b32_e32 v46, v35
	s_waitcnt vmcnt(7)
	v_pk_add_f32 v[8:9], v[50:51], 1.0 op_sel_hi:[1,0]
	v_pk_add_f32 v[12:13], v[48:49], 1.0 op_sel_hi:[1,0]
	v_pk_mul_f32 v[8:9], v[4:5], v[8:9]
	v_pk_mul_f32 v[12:13], v[2:3], v[12:13]
	v_cvt_pk_f16_f32 v9, v8, v9
	v_cvt_pk_f16_f32 v8, v12, v13
	ds_write2st64_b64 v228, v[10:11], v[8:9] offset0:32 offset1:40
	s_waitcnt vmcnt(6)
	v_cvt_pk_f16_f32 v9, v54, v55
	s_waitcnt vmcnt(5)
	v_pk_add_f32 v[10:11], v[58:59], 1.0 op_sel_hi:[1,0]
	v_pk_add_f32 v[12:13], v[56:57], 1.0 op_sel_hi:[1,0]
	v_pk_mul_f32 v[10:11], v[4:5], v[10:11]
	v_pk_mul_f32 v[12:13], v[2:3], v[12:13]
	v_cvt_pk_f16_f32 v8, v52, v53
	v_cvt_pk_f16_f32 v11, v10, v11
	v_cvt_pk_f16_f32 v10, v12, v13
	s_waitcnt vmcnt(4)
	v_cvt_pk_f16_f32 v13, v62, v63
	v_cvt_pk_f16_f32 v12, v60, v61
	ds_write2st64_b64 v228, v[8:9], v[12:13] offset0:112 offset1:120
	s_waitcnt vmcnt(3)
	v_pk_add_f32 v[8:9], v[66:67], 1.0 op_sel_hi:[1,0]
	v_pk_add_f32 v[12:13], v[64:65], 1.0 op_sel_hi:[1,0]
	v_pk_mul_f32 v[8:9], v[4:5], v[8:9]
	v_pk_mul_f32 v[12:13], v[2:3], v[12:13]
	v_cvt_pk_f16_f32 v9, v8, v9
	v_cvt_pk_f16_f32 v8, v12, v13
	ds_write2st64_b64 v228, v[10:11], v[8:9] offset0:48 offset1:56
	s_waitcnt vmcnt(1)
	v_pk_add_f32 v[10:11], v[74:75], 1.0 op_sel_hi:[1,0]
	v_pk_add_f32 v[12:13], v[72:73], 1.0 op_sel_hi:[1,0]
	v_pk_mul_f32 v[4:5], v[4:5], v[10:11]
	v_pk_mul_f32 v[2:3], v[2:3], v[12:13]
	v_cvt_pk_f16_f32 v9, v70, v71
	v_cvt_pk_f16_f32 v8, v68, v69
	v_cvt_pk_f16_f32 v5, v4, v5
	v_cvt_pk_f16_f32 v4, v2, v3
	s_waitcnt vmcnt(0)
	v_cvt_pk_f16_f32 v3, v78, v79
	v_cvt_pk_f16_f32 v2, v76, v77
	ds_write2st64_b64 v34, v[8:9], v[2:3] offset0:56 offset1:64
	v_lshlrev_b32_e32 v2, 4, v1
	v_mov_b32_e32 v34, v35
	v_mov_b32_e32 v68, v35
	v_mov_b32_e32 v69, v35
	v_mov_b32_e32 v62, v35
	v_mov_b32_e32 v63, v35
	v_mov_b32_e32 v66, v35
	v_mov_b32_e32 v67, v35
	v_mov_b32_e32 v60, v35
	v_mov_b32_e32 v61, v35
	v_mov_b32_e32 v64, v35
	v_mov_b32_e32 v65, v35
	v_mov_b32_e32 v58, v35
	v_mov_b32_e32 v59, v35
	v_mov_b32_e32 v56, v35
	v_mov_b32_e32 v57, v35
	v_mov_b32_e32 v48, v35
	v_mov_b32_e32 v49, v35
	v_mov_b32_e32 v54, v35
	v_mov_b32_e32 v55, v35
	v_mov_b32_e32 v47, v35
	v_mov_b32_e32 v52, v35
	v_mov_b32_e32 v53, v35
	v_mov_b32_e32 v44, v35
	v_mov_b32_e32 v45, v35
	v_mov_b32_e32 v50, v35
	v_mov_b32_e32 v51, v35
	v_mov_b32_e32 v40, v35
	v_mov_b32_e32 v41, v35
	v_mov_b32_e32 v42, v35
	v_mov_b32_e32 v43, v35
	v_readlane_b32 s13, v253, 19
	v_readlane_b32 s14, v253, 20
	v_readlane_b32 s15, v253, 21
	v_readlane_b32 s18, v253, 24
	v_readlane_b32 s19, v253, 25
	ds_write2st64_b64 v228, v[4:5], v[6:7] offset0:64 offset1:72
	s_cbranch_scc1 .LBB0_2363
	s_ashr_i32 s9, s8, 31
	s_lshl_b64 s[4:5], s[8:9], 12
	v_readlane_b32 s6, v253, 52
	v_readlane_b32 s7, v253, 53
	s_add_u32 s4, s6, s4
	s_addc_u32 s5, s7, s5
	global_load_dwordx4 v[4:7], v2, s[4:5] nt
	global_load_dwordx4 v[8:11], v2, s[4:5] offset:1024 nt
	global_load_dwordx4 v[12:15], v2, s[4:5] offset:2048 nt
	global_load_dwordx4 v[16:19], v2, s[4:5] offset:3072 nt
	s_waitcnt vmcnt(3)
	v_cvt_f32_f16_e32 v34, v4
	v_cvt_f32_f16_sdwa v35, v4 dst_sel:DWORD dst_unused:UNUSED_PAD src0_sel:WORD_1
	v_cvt_f32_f16_e32 v68, v5
	v_cvt_f32_f16_sdwa v69, v5 dst_sel:DWORD dst_unused:UNUSED_PAD src0_sel:WORD_1
	v_cvt_f32_f16_e32 v62, v6
	v_cvt_f32_f16_sdwa v63, v6 dst_sel:DWORD dst_unused:UNUSED_PAD src0_sel:WORD_1
	v_cvt_f32_f16_e32 v66, v7
	v_cvt_f32_f16_sdwa v67, v7 dst_sel:DWORD dst_unused:UNUSED_PAD src0_sel:WORD_1
	s_waitcnt vmcnt(2)
	v_cvt_f32_f16_e32 v60, v8
	v_cvt_f32_f16_sdwa v61, v8 dst_sel:DWORD dst_unused:UNUSED_PAD src0_sel:WORD_1
	v_cvt_f32_f16_e32 v64, v9
	v_cvt_f32_f16_sdwa v65, v9 dst_sel:DWORD dst_unused:UNUSED_PAD src0_sel:WORD_1
	v_cvt_f32_f16_e32 v58, v10
	v_cvt_f32_f16_sdwa v59, v10 dst_sel:DWORD dst_unused:UNUSED_PAD src0_sel:WORD_1
	v_cvt_f32_f16_e32 v56, v11
	v_cvt_f32_f16_sdwa v57, v11 dst_sel:DWORD dst_unused:UNUSED_PAD src0_sel:WORD_1
	s_waitcnt vmcnt(1)
	v_cvt_f32_f16_e32 v48, v12
	v_cvt_f32_f16_sdwa v49, v12 dst_sel:DWORD dst_unused:UNUSED_PAD src0_sel:WORD_1
	v_cvt_f32_f16_e32 v54, v13
	v_cvt_f32_f16_sdwa v55, v13 dst_sel:DWORD dst_unused:UNUSED_PAD src0_sel:WORD_1
	v_cvt_f32_f16_e32 v46, v14
	v_cvt_f32_f16_sdwa v47, v14 dst_sel:DWORD dst_unused:UNUSED_PAD src0_sel:WORD_1
	v_cvt_f32_f16_e32 v52, v15
	v_cvt_f32_f16_sdwa v53, v15 dst_sel:DWORD dst_unused:UNUSED_PAD src0_sel:WORD_1
	s_waitcnt vmcnt(0)
	v_cvt_f32_f16_e32 v44, v16
	v_cvt_f32_f16_sdwa v45, v16 dst_sel:DWORD dst_unused:UNUSED_PAD src0_sel:WORD_1
	v_cvt_f32_f16_e32 v50, v17
	v_cvt_f32_f16_sdwa v51, v17 dst_sel:DWORD dst_unused:UNUSED_PAD src0_sel:WORD_1
	v_cvt_f32_f16_e32 v40, v18
	v_cvt_f32_f16_sdwa v41, v18 dst_sel:DWORD dst_unused:UNUSED_PAD src0_sel:WORD_1
	v_cvt_f32_f16_e32 v42, v19
	v_cvt_f32_f16_sdwa v43, v19 dst_sel:DWORD dst_unused:UNUSED_PAD src0_sel:WORD_1

; #define GAS __attribute__((address_space(1)))
;     __device__ __forceinline__ void operator()(const f32x4 (&acc)[2][2][4][2], const pg8::Unit& u, int wr, int wc, int fr, int fq) const {
;     ...
;         const float* gv = gate + (size_t)r * DMODW + col0;
;         f32x4 gvv[2][2];
; #pragma unroll
;         for (int bj = 0; bj < 2; ++bj)
; #pragma unroll
;             for (int n = 0; n < 2; ++n) gvv[bj][n] = *(const f32x4*)(gv + bj * 128 + 4 * n) * coef;
;         if (u.kind >= 2) {
;             GAS float* op = part + (size_t)(u.kind - 2) * (PART_STRIDE / 4) + (size_t)(row0 - M_LAT) * D + col0;
; #pragma unroll
;             for (int ai = 0; ai < 2; ++ai)
; #pragma unroll
;                 for (int m = 0; m < 4; ++m) { const size_t ro = (size_t)(ai * 128 + m * 16) * D;
; #pragma unroll
;                     for (int bj = 0; bj < 2; ++bj)
; #pragma unroll
;                         for (int n = 0; n < 2; ++n) *(GAS f32x4*)(op + ro + bj * 128 + 4 * n) = gvv[bj][n] * acc[ai][bj][m][n]; }
;             return;
;         }
;         const size_t eo = (u.pm < 64 ? (size_t)row0 : (size_t)(row0 - M_LAT)) * D + col0;
;         const void* bsel = u.pm < 64 ? base_lat : base_ctx;
;         const size_t oo = (size_t)row0 * D + col0;
;         if constexpr (!BASE_F32) {
;             u32x4 hb[2][4][2];
; #pragma unroll
;             for (int ai = 0; ai < 2; ++ai)
; #pragma unroll
;                 for (int m = 0; m < 4; ++m)
; #pragma unroll
;                     for (int bj = 0; bj < 2; ++bj) hb[ai][m][bj] = *(const u32x4*)((const _Float16*)bsel + eo + (size_t)(ai * 128 + m * 16) * D + bj * 128);
; #pragma unroll
;             for (int ai = 0; ai < 2; ++ai)
; #pragma unroll
;                 for (int m = 0; m < 4; ++m)
; #pragma unroll
;                     for (int bj = 0; bj < 2; ++bj) { const size_t ro = (size_t)(ai * 128 + m * 16) * D + bj * 128; const u32x4 hv = hb[ai][m][bj];
;                         const f32x4 v0 = h4_to_f32x4((u32x2){hv.x, hv.y}) + gvv[bj][0] * acc[ai][bj][m][0], v1 = h4_to_f32x4((u32x2){hv.z, hv.w}) + gvv[bj][1] * acc[ai][bj][m][1];
;                         if constexpr (OUT_F32) { *(f32x4*)((float*)out + oo + ro) = v0; *(f32x4*)((float*)out + oo + ro + 4) = v1; }
;                         else { const u32x2 h0 = f32x4_to_h4(v0), h1 = f32x4_to_h4(v1); *(u32x4*)((_Float16*)out + oo + ro) = (u32x4){h0.x, h0.y, h1.x, h1.y}; } }
.LBB0_2522:
	s_add_u32 s18, s88, s18
	v_lshl_or_b32 v2, s53, 8, v205
	s_addc_u32 s19, s89, s19
	s_lshl_b64 s[16:17], s[16:17], 2
	v_ashrrev_i32_e32 v3, 31, v2
	s_add_u32 s16, s33, s16
	v_lshl_add_u32 v0, s54, 8, v203
	s_addc_u32 s17, s34, s17
	v_lshlrev_b64 v[4:5], 2, v[2:3]
	v_lshl_add_u64 v[6:7], s[16:17], 0, v[4:5]
	v_add_u32_e32 v1, 0xffffc000, v0
	global_load_dwordx4 v[184:187], v[6:7], off offset:16
	global_load_dwordx4 v[190:193], v[6:7], off
	global_load_dwordx4 v[210:213], v[6:7], off offset:528
	global_load_dwordx4 v[214:217], v[6:7], off offset:512
	v_cndmask_b32_e32 v6, v1, v0, vcc
	v_ashrrev_i32_e32 v7, 31, v6
	v_lshlrev_b64 v[6:7], 12, v[6:7]
	v_lshl_add_u64 v[6:7], s[18:19], 0, v[6:7]
	v_lshl_add_u64 v[2:3], v[2:3], 1, v[6:7]
	global_load_dwordx4 v[218:221], v[2:3], off
	global_load_dwordx4 v[222:225], v[2:3], off offset:256
	v_add_co_u32_e32 v6, vcc, s31, v2
	v_ashrrev_i32_e32 v1, 31, v0
	s_nop 0
	v_addc_co_u32_e32 v7, vcc, 0, v3, vcc
	global_load_dwordx4 v[226:229], v[6:7], off
	global_load_dwordx4 v[230:233], v[6:7], off offset:256
	v_readlane_b32 s56, v253, 0
	v_lshlrev_b64 v[0:1], 13, v[0:1]
	v_readlane_b32 s62, v253, 6
	v_readlane_b32 s63, v253, 7
	v_readlane_b32 s57, v253, 1
	v_readlane_b32 s58, v253, 2
	v_lshl_add_u64 v[0:1], s[62:63], 0, v[0:1]
	v_lshl_add_u64 v[188:189], v[0:1], 0, v[4:5]
	v_add_co_u32_e32 v0, vcc, s40, v2
	v_readlane_b32 s59, v253, 3
	s_nop 0
	v_addc_co_u32_e32 v1, vcc, 0, v3, vcc
	v_add_co_u32_e32 v4, vcc, s41, v2
	v_readlane_b32 s60, v253, 4
	s_nop 0
	v_addc_co_u32_e32 v5, vcc, 0, v3, vcc
	v_add_co_u32_e32 v6, vcc, s42, v2
	v_readlane_b32 s61, v253, 5
	s_nop 0
	v_addc_co_u32_e32 v7, vcc, 0, v3, vcc
	v_add_co_u32_e32 v8, vcc, s43, v2
	s_waitcnt vmcnt(0)
	v_pk_mul_f32 v[196:197], v[186:187], s[12:13] op_sel_hi:[1,0]
	v_addc_co_u32_e32 v9, vcc, 0, v3, vcc
	v_add_co_u32_e32 v10, vcc, s44, v2
	v_pk_mul_f32 v[198:199], v[192:193], s[12:13] op_sel_hi:[1,0]
	s_nop 0
	v_addc_co_u32_e32 v11, vcc, 0, v3, vcc
	v_add_co_u32_e32 v2, vcc, s45, v2
	v_pk_mul_f32 v[194:195], v[184:185], s[12:13] op_sel_hi:[1,0]
	s_nop 0
	v_addc_co_u32_e32 v3, vcc, 0, v3, vcc
	global_load_dwordx4 v[234:237], v[0:1], off
	global_load_dwordx4 v[238:241], v[0:1], off offset:256
	global_load_dwordx4 v[164:167], v[4:5], off
	global_load_dwordx4 v[160:163], v[4:5], off offset:256
	global_load_dwordx4 v[28:31], v[6:7], off
	global_load_dwordx4 v[24:27], v[6:7], off offset:256
	global_load_dwordx4 v[20:23], v[8:9], off
	global_load_dwordx4 v[16:19], v[8:9], off offset:256
	global_load_dwordx4 v[12:15], v[10:11], off
	s_nop 0
	global_load_dwordx4 v[8:11], v[10:11], off offset:256
	s_nop 0
	global_load_dwordx4 v[4:7], v[2:3], off
	s_nop 0
	global_load_dwordx4 v[0:3], v[2:3], off offset:256
	v_pk_mul_f32 v[192:193], v[214:215], s[12:13] op_sel_hi:[1,0]
	v_pk_mul_f32 v[186:187], v[212:213], s[12:13] op_sel_hi:[1,0]
	v_pk_mul_f32 v[184:185], v[210:211], s[12:13] op_sel_hi:[1,0]
	v_cvt_f32_f16_e32 v210, v218
	v_cvt_f32_f16_sdwa v211, v218 dst_sel:DWORD dst_unused:UNUSED_PAD src0_sel:WORD_1
	v_cvt_f32_f16_e32 v212, v219
	v_cvt_f32_f16_sdwa v213, v219 dst_sel:DWORD dst_unused:UNUSED_PAD src0_sel:WORD_1
	v_cvt_f32_f16_e32 v214, v220
	v_cvt_f32_f16_sdwa v215, v220 dst_sel:DWORD dst_unused:UNUSED_PAD src0_sel:WORD_1
	v_pk_mul_f32 v[200:201], v[190:191], s[12:13] op_sel_hi:[1,0]
	v_pk_mul_f32 v[190:191], v[216:217], s[12:13] op_sel_hi:[1,0]
	v_cvt_f32_f16_e32 v216, v221
	v_cvt_f32_f16_sdwa v217, v221 dst_sel:DWORD dst_unused:UNUSED_PAD src0_sel:WORD_1
	v_pk_fma_f32 v[158:159], v[158:159], v[198:199], v[212:213]
	v_pk_fma_f32 v[156:157], v[156:157], v[200:201], v[210:211]
	v_pk_fma_f32 v[152:153], v[152:153], v[194:195], v[214:215]
	v_cvt_f32_f16_e32 v218, v222
	v_cvt_f32_f16_sdwa v219, v222 dst_sel:DWORD dst_unused:UNUSED_PAD src0_sel:WORD_1
	v_cvt_f32_f16_e32 v220, v223
	v_pk_fma_f32 v[154:155], v[154:155], v[196:197], v[216:217]
	global_store_dwordx4 v[188:189], v[156:159], off nt
	global_store_dwordx4 v[188:189], v[152:155], off offset:16 nt
	v_cvt_f32_f16_sdwa v221, v223 dst_sel:DWORD dst_unused:UNUSED_PAD src0_sel:WORD_1
	v_pk_fma_f32 v[148:149], v[148:149], v[192:193], v[218:219]
	v_cvt_f32_f16_e32 v152, v224
	v_cvt_f32_f16_sdwa v153, v224 dst_sel:DWORD dst_unused:UNUSED_PAD src0_sel:WORD_1
	v_cvt_f32_f16_e32 v154, v225
	v_cvt_f32_f16_sdwa v155, v225 dst_sel:DWORD dst_unused:UNUSED_PAD src0_sel:WORD_1
	v_pk_fma_f32 v[150:151], v[150:151], v[190:191], v[220:221]
	v_pk_fma_f32 v[144:145], v[144:145], v[184:185], v[152:153]
	v_pk_fma_f32 v[146:147], v[146:147], v[186:187], v[154:155]
	global_store_dwordx4 v[188:189], v[148:151], off offset:512 nt
	global_store_dwordx4 v[188:189], v[144:147], off offset:528 nt
	s_nop 0
	v_cvt_f32_f16_e32 v148, v228
	v_cvt_f32_f16_e32 v144, v226
	v_cvt_f32_f16_sdwa v145, v226 dst_sel:DWORD dst_unused:UNUSED_PAD src0_sel:WORD_1
	v_cvt_f32_f16_e32 v146, v227
	v_cvt_f32_f16_sdwa v147, v227 dst_sel:DWORD dst_unused:UNUSED_PAD src0_sel:WORD_1
	v_cvt_f32_f16_e32 v150, v229
	v_cvt_f32_f16_sdwa v151, v229 dst_sel:DWORD dst_unused:UNUSED_PAD src0_sel:WORD_1
	v_cvt_f32_f16_sdwa v149, v228 dst_sel:DWORD dst_unused:UNUSED_PAD src0_sel:WORD_1
	v_pk_fma_f32 v[140:141], v[140:141], v[200:201], v[144:145]
	v_add_co_u32_e32 v144, vcc, s40, v188
	v_pk_fma_f32 v[142:143], v[142:143], v[198:199], v[146:147]
	v_pk_fma_f32 v[138:139], v[138:139], v[196:197], v[150:151]
	v_pk_fma_f32 v[136:137], v[136:137], v[194:195], v[148:149]
	v_addc_co_u32_e32 v145, vcc, 0, v189, vcc
	global_store_dwordx4 v[144:145], v[140:143], off nt
	global_store_dwordx4 v[144:145], v[136:139], off offset:16 nt
	s_nop 0
	v_cvt_f32_f16_e32 v140, v232
	v_cvt_f32_f16_e32 v136, v230
	v_cvt_f32_f16_sdwa v137, v230 dst_sel:DWORD dst_unused:UNUSED_PAD src0_sel:WORD_1
	v_cvt_f32_f16_e32 v138, v231
	v_cvt_f32_f16_sdwa v139, v231 dst_sel:DWORD dst_unused:UNUSED_PAD src0_sel:WORD_1
	v_cvt_f32_f16_sdwa v141, v232 dst_sel:DWORD dst_unused:UNUSED_PAD src0_sel:WORD_1
	v_cvt_f32_f16_e32 v142, v233
	v_cvt_f32_f16_sdwa v143, v233 dst_sel:DWORD dst_unused:UNUSED_PAD src0_sel:WORD_1
	v_pk_fma_f32 v[134:135], v[134:135], v[190:191], v[138:139]
	v_pk_fma_f32 v[132:133], v[132:133], v[192:193], v[136:137]
	v_pk_fma_f32 v[128:129], v[128:129], v[184:185], v[140:141]
	v_pk_fma_f32 v[130:131], v[130:131], v[186:187], v[142:143]
	global_store_dwordx4 v[144:145], v[132:135], off offset:512 nt
	global_store_dwordx4 v[144:145], v[128:131], off offset:528 nt
	s_waitcnt vmcnt(19)
; __device__ __forceinline__ u32x2 f32x4_to_h4(f32x4 v) { return __builtin_bit_cast(u32x2, __builtin_convertvector(v, f16x4)); }
; __device__ __forceinline__ f32x4 h4_to_f32x4(u32x2 v) { return __builtin_convertvector(__builtin_bit_cast(f16x4, v), f32x4); }
;     __device__ __forceinline__ void operator()(const f32x4 (&acc)[2][2][4][2], const pg8::Unit& u, int wr, int wc, int fr, int fq) const {
;     ...
;                     for (int bj = 0; bj < 2; ++bj) { const size_t ro = (size_t)(ai * 128 + m * 16) * D + bj * 128; const u32x4 hv = hb[ai][m][bj];
;                         const f32x4 v0 = h4_to_f32x4((u32x2){hv.x, hv.y}) + gvv[bj][0] * acc[ai][bj][m][0], v1 = h4_to_f32x4((u32x2){hv.z, hv.w}) + gvv[bj][1] * acc[ai][bj][m][1];
;                         if constexpr (OUT_F32) { *(f32x4*)((float*)out + oo + ro) = v0; *(f32x4*)((float*)out + oo + ro + 4) = v1; }
;                         else { const u32x2 h0 = f32x4_to_h4(v0), h1 = f32x4_to_h4(v1); *(u32x4*)((_Float16*)out + oo + ro) = (u32x4){h0.x, h0.y, h1.x, h1.y}; } }
	v_cvt_f32_f16_e32 v132, v236
	v_cvt_f32_f16_e32 v128, v234
	v_cvt_f32_f16_sdwa v129, v234 dst_sel:DWORD dst_unused:UNUSED_PAD src0_sel:WORD_1
	v_cvt_f32_f16_e32 v130, v235
	v_cvt_f32_f16_sdwa v131, v235 dst_sel:DWORD dst_unused:UNUSED_PAD src0_sel:WORD_1
	v_cvt_f32_f16_e32 v134, v237
	v_cvt_f32_f16_sdwa v135, v237 dst_sel:DWORD dst_unused:UNUSED_PAD src0_sel:WORD_1
	v_cvt_f32_f16_sdwa v133, v236 dst_sel:DWORD dst_unused:UNUSED_PAD src0_sel:WORD_1
	v_pk_fma_f32 v[124:125], v[124:125], v[200:201], v[128:129]
	v_add_co_u32_e32 v128, vcc, s46, v188
	v_pk_fma_f32 v[126:127], v[126:127], v[198:199], v[130:131]
	v_pk_fma_f32 v[122:123], v[122:123], v[196:197], v[134:135]
	v_pk_fma_f32 v[120:121], v[120:121], v[194:195], v[132:133]
	v_addc_co_u32_e32 v129, vcc, 0, v189, vcc
	global_store_dwordx4 v[128:129], v[124:127], off nt
	global_store_dwordx4 v[128:129], v[120:123], off offset:16 nt
	s_waitcnt vmcnt(20)
	v_cvt_f32_f16_e32 v124, v240
	v_cvt_f32_f16_e32 v120, v238
	v_cvt_f32_f16_sdwa v121, v238 dst_sel:DWORD dst_unused:UNUSED_PAD src0_sel:WORD_1
	v_cvt_f32_f16_e32 v122, v239
	v_cvt_f32_f16_sdwa v123, v239 dst_sel:DWORD dst_unused:UNUSED_PAD src0_sel:WORD_1
	v_cvt_f32_f16_sdwa v125, v240 dst_sel:DWORD dst_unused:UNUSED_PAD src0_sel:WORD_1
	v_cvt_f32_f16_e32 v126, v241
	v_cvt_f32_f16_sdwa v127, v241 dst_sel:DWORD dst_unused:UNUSED_PAD src0_sel:WORD_1
	v_pk_fma_f32 v[118:119], v[118:119], v[190:191], v[122:123]
	v_pk_fma_f32 v[116:117], v[116:117], v[192:193], v[120:121]
	v_pk_fma_f32 v[112:113], v[112:113], v[184:185], v[124:125]
	v_pk_fma_f32 v[114:115], v[114:115], v[186:187], v[126:127]
	global_store_dwordx4 v[128:129], v[116:119], off offset:512 nt
	global_store_dwordx4 v[128:129], v[112:115], off offset:528 nt
	s_waitcnt vmcnt(21)
	v_cvt_f32_f16_e32 v116, v166
	v_cvt_f32_f16_e32 v112, v164
	v_cvt_f32_f16_sdwa v113, v164 dst_sel:DWORD dst_unused:UNUSED_PAD src0_sel:WORD_1
	v_cvt_f32_f16_e32 v114, v165
	v_cvt_f32_f16_sdwa v115, v165 dst_sel:DWORD dst_unused:UNUSED_PAD src0_sel:WORD_1
	v_cvt_f32_f16_e32 v118, v167
	v_cvt_f32_f16_sdwa v119, v167 dst_sel:DWORD dst_unused:UNUSED_PAD src0_sel:WORD_1
	v_cvt_f32_f16_sdwa v117, v166 dst_sel:DWORD dst_unused:UNUSED_PAD src0_sel:WORD_1
	v_pk_fma_f32 v[108:109], v[108:109], v[200:201], v[112:113]
	v_add_co_u32_e32 v112, vcc, s47, v188
	v_pk_fma_f32 v[110:111], v[110:111], v[198:199], v[114:115]
	v_pk_fma_f32 v[106:107], v[106:107], v[196:197], v[118:119]
	v_pk_fma_f32 v[104:105], v[104:105], v[194:195], v[116:117]
	v_addc_co_u32_e32 v113, vcc, 0, v189, vcc
	global_store_dwordx4 v[112:113], v[108:111], off nt
	global_store_dwordx4 v[112:113], v[104:107], off offset:16 nt
	s_waitcnt vmcnt(22)
	v_cvt_f32_f16_e32 v108, v162
	v_cvt_f32_f16_e32 v104, v160
	v_cvt_f32_f16_sdwa v105, v160 dst_sel:DWORD dst_unused:UNUSED_PAD src0_sel:WORD_1
	v_cvt_f32_f16_e32 v106, v161
	v_cvt_f32_f16_sdwa v107, v161 dst_sel:DWORD dst_unused:UNUSED_PAD src0_sel:WORD_1
	v_cvt_f32_f16_sdwa v109, v162 dst_sel:DWORD dst_unused:UNUSED_PAD src0_sel:WORD_1
	v_cvt_f32_f16_e32 v110, v163
	v_cvt_f32_f16_sdwa v111, v163 dst_sel:DWORD dst_unused:UNUSED_PAD src0_sel:WORD_1
	v_pk_fma_f32 v[102:103], v[102:103], v[190:191], v[106:107]
	v_pk_fma_f32 v[100:101], v[100:101], v[192:193], v[104:105]
	v_pk_fma_f32 v[96:97], v[96:97], v[184:185], v[108:109]
	v_pk_fma_f32 v[98:99], v[98:99], v[186:187], v[110:111]
	global_store_dwordx4 v[112:113], v[100:103], off offset:512 nt
	global_store_dwordx4 v[112:113], v[96:99], off offset:528 nt
	s_waitcnt vmcnt(23)
	v_cvt_f32_f16_e32 v100, v31
	v_cvt_f32_f16_e32 v96, v28
	v_cvt_f32_f16_sdwa v97, v28 dst_sel:DWORD dst_unused:UNUSED_PAD src0_sel:WORD_1
	v_cvt_f32_f16_e32 v28, v29
	v_cvt_f32_f16_sdwa v29, v29 dst_sel:DWORD dst_unused:UNUSED_PAD src0_sel:WORD_1
	v_cvt_f32_f16_e32 v98, v30
	v_cvt_f32_f16_sdwa v99, v30 dst_sel:DWORD dst_unused:UNUSED_PAD src0_sel:WORD_1
	v_cvt_f32_f16_sdwa v101, v31 dst_sel:DWORD dst_unused:UNUSED_PAD src0_sel:WORD_1
	v_pk_fma_f32 v[30:31], v[94:95], v[198:199], v[28:29]
	v_pk_fma_f32 v[28:29], v[92:93], v[200:201], v[96:97]
	v_add_co_u32_e32 v92, vcc, s48, v188
	v_pk_fma_f32 v[88:89], v[88:89], v[194:195], v[98:99]
	s_nop 0
	v_addc_co_u32_e32 v93, vcc, 0, v189, vcc
	v_pk_fma_f32 v[90:91], v[90:91], v[196:197], v[100:101]
	global_store_dwordx4 v[92:93], v[28:31], off nt
	global_store_dwordx4 v[92:93], v[88:91], off offset:16 nt
	s_waitcnt vmcnt(24)
	v_cvt_f32_f16_e32 v28, v24
	v_cvt_f32_f16_sdwa v29, v24 dst_sel:DWORD dst_unused:UNUSED_PAD src0_sel:WORD_1
	v_cvt_f32_f16_e32 v24, v25
	v_cvt_f32_f16_sdwa v25, v25 dst_sel:DWORD dst_unused:UNUSED_PAD src0_sel:WORD_1
	v_cvt_f32_f16_e32 v88, v26
	v_cvt_f32_f16_sdwa v89, v26 dst_sel:DWORD dst_unused:UNUSED_PAD src0_sel:WORD_1
	v_cvt_f32_f16_e32 v30, v27
	v_cvt_f32_f16_sdwa v31, v27 dst_sel:DWORD dst_unused:UNUSED_PAD src0_sel:WORD_1
	v_pk_fma_f32 v[26:27], v[86:87], v[190:191], v[24:25]
	v_pk_fma_f32 v[24:25], v[84:85], v[192:193], v[28:29]
	v_pk_fma_f32 v[28:29], v[80:81], v[184:185], v[88:89]
	v_pk_fma_f32 v[30:31], v[82:83], v[186:187], v[30:31]
	global_store_dwordx4 v[92:93], v[24:27], off offset:512 nt
	global_store_dwordx4 v[92:93], v[28:31], off offset:528 nt
	s_waitcnt vmcnt(25)
; #define PG8_BAR __builtin_amdgcn_s_barrier()
; __device__ __forceinline__ u32x2 f32x4_to_h4(f32x4 v) { return __builtin_bit_cast(u32x2, __builtin_convertvector(v, f16x4)); }
; __device__ __forceinline__ f32x4 h4_to_f32x4(u32x2 v) { return __builtin_convertvector(__builtin_bit_cast(f16x4, v), f32x4); }
; template <class Epi, class Sched, bool ALIGN_EPI = true, bool SP2 = true>
; __device__ __forceinline__ void gemm_phase(PG8_LAS unsigned char* lds, const int K  , const Sched& S, const Epi& E) {
;     ...
;         if constexpr (ALIGN_EPI) { if (wr == 0) PG8_BAR; }
;         E(acc, cur, wr, wc, fr, fq);
;         if (!has_next) break;
; #pragma unroll
;         for (int a = 0; a < 2; ++a)
; #pragma unroll
;             for (int b = 0; b < 2; ++b)
; #pragma unroll
;                 for (int m = 0; m < 4; ++m)
; #pragma unroll
;                     for (int n = 0; n < 2; ++n) acc[a][b][m][n] = (f32x4){0.f, 0.f, 0.f, 0.f};
;         cur = nxt; cA = nA; cB = nB; ++ui;
;         if constexpr (ALIGN_EPI) { if (wr == 1) PG8_BAR; }
;     __device__ __forceinline__ void operator()(const f32x4 (&acc)[2][2][4][2], const pg8::Unit& u, int wr, int wc, int fr, int fq) const {
;     ...
;                     for (int bj = 0; bj < 2; ++bj) { const size_t ro = (size_t)(ai * 128 + m * 16) * D + bj * 128; const u32x4 hv = hb[ai][m][bj];
;                         const f32x4 v0 = h4_to_f32x4((u32x2){hv.x, hv.y}) + gvv[bj][0] * acc[ai][bj][m][0], v1 = h4_to_f32x4((u32x2){hv.z, hv.w}) + gvv[bj][1] * acc[ai][bj][m][1];
;                         if constexpr (OUT_F32) { *(f32x4*)((float*)out + oo + ro) = v0; *(f32x4*)((float*)out + oo + ro + 4) = v1; }
;                         else { const u32x2 h0 = f32x4_to_h4(v0), h1 = f32x4_to_h4(v1); *(u32x4*)((_Float16*)out + oo + ro) = (u32x4){h0.x, h0.y, h1.x, h1.y}; } }
	v_cvt_f32_f16_e32 v24, v20
	v_cvt_f32_f16_sdwa v25, v20 dst_sel:DWORD dst_unused:UNUSED_PAD src0_sel:WORD_1
	v_cvt_f32_f16_e32 v20, v21
	v_cvt_f32_f16_sdwa v21, v21 dst_sel:DWORD dst_unused:UNUSED_PAD src0_sel:WORD_1
	v_cvt_f32_f16_e32 v28, v22
	v_cvt_f32_f16_sdwa v29, v22 dst_sel:DWORD dst_unused:UNUSED_PAD src0_sel:WORD_1
	v_cvt_f32_f16_e32 v26, v23
	v_cvt_f32_f16_sdwa v27, v23 dst_sel:DWORD dst_unused:UNUSED_PAD src0_sel:WORD_1
	v_pk_fma_f32 v[22:23], v[78:79], v[198:199], v[20:21]
	v_pk_fma_f32 v[20:21], v[76:77], v[200:201], v[24:25]
	v_pk_fma_f32 v[24:25], v[72:73], v[194:195], v[28:29]
	v_add_co_u32_e32 v28, vcc, s49, v188
	v_pk_fma_f32 v[26:27], v[74:75], v[196:197], v[26:27]
	s_nop 0
	v_addc_co_u32_e32 v29, vcc, 0, v189, vcc
	global_store_dwordx4 v[28:29], v[20:23], off nt
	global_store_dwordx4 v[28:29], v[24:27], off offset:16 nt
	s_waitcnt vmcnt(26)
	v_cvt_f32_f16_e32 v20, v16
	v_cvt_f32_f16_sdwa v21, v16 dst_sel:DWORD dst_unused:UNUSED_PAD src0_sel:WORD_1
	v_cvt_f32_f16_e32 v16, v17
	v_cvt_f32_f16_sdwa v17, v17 dst_sel:DWORD dst_unused:UNUSED_PAD src0_sel:WORD_1
	v_cvt_f32_f16_e32 v24, v18
	v_cvt_f32_f16_sdwa v25, v18 dst_sel:DWORD dst_unused:UNUSED_PAD src0_sel:WORD_1
	v_cvt_f32_f16_e32 v22, v19
	v_cvt_f32_f16_sdwa v23, v19 dst_sel:DWORD dst_unused:UNUSED_PAD src0_sel:WORD_1
	v_pk_fma_f32 v[18:19], v[70:71], v[190:191], v[16:17]
	v_pk_fma_f32 v[16:17], v[68:69], v[192:193], v[20:21]
	v_pk_fma_f32 v[20:21], v[64:65], v[184:185], v[24:25]
	v_pk_fma_f32 v[22:23], v[66:67], v[186:187], v[22:23]
	global_store_dwordx4 v[28:29], v[16:19], off offset:512 nt
	global_store_dwordx4 v[28:29], v[20:23], off offset:528 nt
	s_waitcnt vmcnt(27)
	v_cvt_f32_f16_e32 v16, v12
	v_cvt_f32_f16_sdwa v17, v12 dst_sel:DWORD dst_unused:UNUSED_PAD src0_sel:WORD_1
	v_cvt_f32_f16_e32 v12, v13
	v_cvt_f32_f16_sdwa v13, v13 dst_sel:DWORD dst_unused:UNUSED_PAD src0_sel:WORD_1
	v_cvt_f32_f16_e32 v20, v14
	v_cvt_f32_f16_sdwa v21, v14 dst_sel:DWORD dst_unused:UNUSED_PAD src0_sel:WORD_1
	v_cvt_f32_f16_e32 v18, v15
	v_cvt_f32_f16_sdwa v19, v15 dst_sel:DWORD dst_unused:UNUSED_PAD src0_sel:WORD_1
	v_pk_fma_f32 v[14:15], v[62:63], v[198:199], v[12:13]
	v_pk_fma_f32 v[12:13], v[60:61], v[200:201], v[16:17]
	v_pk_fma_f32 v[16:17], v[56:57], v[194:195], v[20:21]
	v_add_co_u32_e32 v20, vcc, s50, v188
	v_pk_fma_f32 v[18:19], v[58:59], v[196:197], v[18:19]
	s_nop 0
	v_addc_co_u32_e32 v21, vcc, 0, v189, vcc
	global_store_dwordx4 v[20:21], v[12:15], off nt
	global_store_dwordx4 v[20:21], v[16:19], off offset:16 nt
	s_waitcnt vmcnt(28)
	v_cvt_f32_f16_e32 v12, v8
	v_cvt_f32_f16_sdwa v13, v8 dst_sel:DWORD dst_unused:UNUSED_PAD src0_sel:WORD_1
	v_cvt_f32_f16_e32 v8, v9
	v_cvt_f32_f16_sdwa v9, v9 dst_sel:DWORD dst_unused:UNUSED_PAD src0_sel:WORD_1
	v_cvt_f32_f16_e32 v16, v10
	v_cvt_f32_f16_sdwa v17, v10 dst_sel:DWORD dst_unused:UNUSED_PAD src0_sel:WORD_1
	v_cvt_f32_f16_e32 v14, v11
	v_cvt_f32_f16_sdwa v15, v11 dst_sel:DWORD dst_unused:UNUSED_PAD src0_sel:WORD_1
	v_pk_fma_f32 v[10:11], v[54:55], v[190:191], v[8:9]
	v_pk_fma_f32 v[8:9], v[52:53], v[192:193], v[12:13]
	v_pk_fma_f32 v[12:13], v[48:49], v[184:185], v[16:17]
	v_pk_fma_f32 v[14:15], v[50:51], v[186:187], v[14:15]
	global_store_dwordx4 v[20:21], v[8:11], off offset:512 nt
	global_store_dwordx4 v[20:21], v[12:15], off offset:528 nt
	s_waitcnt vmcnt(29)
	v_cvt_f32_f16_e32 v8, v4
	v_cvt_f32_f16_sdwa v9, v4 dst_sel:DWORD dst_unused:UNUSED_PAD src0_sel:WORD_1
	v_cvt_f32_f16_e32 v4, v5
	v_cvt_f32_f16_sdwa v5, v5 dst_sel:DWORD dst_unused:UNUSED_PAD src0_sel:WORD_1
	v_cvt_f32_f16_e32 v12, v6
	v_cvt_f32_f16_sdwa v13, v6 dst_sel:DWORD dst_unused:UNUSED_PAD src0_sel:WORD_1
	v_cvt_f32_f16_e32 v10, v7
	v_cvt_f32_f16_sdwa v11, v7 dst_sel:DWORD dst_unused:UNUSED_PAD src0_sel:WORD_1
	v_pk_fma_f32 v[6:7], v[46:47], v[198:199], v[4:5]
	v_pk_fma_f32 v[4:5], v[44:45], v[200:201], v[8:9]
	v_pk_fma_f32 v[8:9], v[40:41], v[194:195], v[12:13]
	v_add_co_u32_e32 v12, vcc, s29, v188
	v_pk_fma_f32 v[10:11], v[42:43], v[196:197], v[10:11]
	s_nop 0
	v_addc_co_u32_e32 v13, vcc, 0, v189, vcc
	global_store_dwordx4 v[12:13], v[4:7], off nt
	global_store_dwordx4 v[12:13], v[8:11], off offset:16 nt
	s_and_b64 vcc, exec, s[0:1]
	s_waitcnt vmcnt(30)
	v_cvt_f32_f16_e32 v4, v0
	v_cvt_f32_f16_sdwa v5, v0 dst_sel:DWORD dst_unused:UNUSED_PAD src0_sel:WORD_1
	v_cvt_f32_f16_e32 v0, v1
	v_cvt_f32_f16_sdwa v1, v1 dst_sel:DWORD dst_unused:UNUSED_PAD src0_sel:WORD_1
	v_cvt_f32_f16_e32 v8, v2
	v_cvt_f32_f16_e32 v6, v3
	v_cvt_f32_f16_sdwa v7, v3 dst_sel:DWORD dst_unused:UNUSED_PAD src0_sel:WORD_1
	v_cvt_f32_f16_sdwa v9, v2 dst_sel:DWORD dst_unused:UNUSED_PAD src0_sel:WORD_1
	v_pk_fma_f32 v[2:3], v[38:39], v[190:191], v[0:1]
	v_pk_fma_f32 v[0:1], v[36:37], v[192:193], v[4:5]
	s_mov_b64 s[0:1], -1
	v_pk_fma_f32 v[6:7], v[34:35], v[186:187], v[6:7]
	v_pk_fma_f32 v[4:5], v[32:33], v[184:185], v[8:9]
	global_store_dwordx4 v[12:13], v[0:3], off offset:512 nt
	global_store_dwordx4 v[12:13], v[4:7], off offset:528 nt
	s_cbranch_vccnz .LBB0_2504
	s_andn2_b64 vcc, exec, s[4:5]
	s_cbranch_vccnz .LBB0_2503
	s_barrier
	s_branch .LBB0_2503
